# merge phase tile body hand-written: 3-stage LDS-DMA ring, fragments read 2 k-steps ahead, gates prefetched
# speedup vs baseline: 1.1090x; 1.0297x over previous
; DI int tidx() { int t = threadIdx.x; asm volatile("" : "+v"(t)); return t; }
; DI void gemm_mid(const bf16_t* __restrict__ W, int ldw, const bf16_t* __restrict__ X, size_t ldx, int mclamp, int kts,
;                  int nkt, int m0, f32x16 (&acc)[2][2], bf16_t* lds) {
;   const int tid = tidx(), lane = tid & 63, wv = tid >> 6, wn = wv & 1, wm = wv >> 1;
;   const int lr = lane & 31, lh = lane >> 5;
;   const int lrow = tid >> 3, lkc = (tid & 7) * 8;
;   const bf16_t* wp = W + (size_t)lrow * ldw + lkc;
;   const size_t wst = (size_t)64 * ldw;
;   const bf16_t *xp0, *xp1, *xp2, *xp3;
;   { int m;
;     m = m0 + lrow;       m = m < mclamp ? m : mclamp; xp0 = X + (size_t)m * ldx + lkc;
;     m = m0 + lrow + 64;  m = m < mclamp ? m : mclamp; xp1 = X + (size_t)m * ldx + lkc;
;     m = m0 + lrow + 128; m = m < mclamp ? m : mclamp; xp2 = X + (size_t)m * ldx + lkc;
;     m = m0 + lrow + 192; m = m < mclamp ? m : mclamp; xp3 = X + (size_t)m * ldx + lkc; }
;   u32x4 rw0, rw1, rx0, rx1, rx2, rx3;
;     ...
;   __syncthreads();
;   GM_GLOAD(0)
;   GM_LSTORE(0)
;   __syncthreads();
; DI void phase_merge(const P& p, int layer, bf16_t* sm, const Geo& ge) {
;     ...
;   while (tw.next(mt_, nt_)) {
;     unsigned zp[2][2][8];
; #pragma unroll
;     for (int a_ = 0; a_ < 2; ++a_)
; #pragma unroll
;       for (int b_ = 0; b_ < 2; ++b_)
; #pragma unroll
;         for (int i = 0; i < 8; ++i) zp[a_][b_][i] = 0u;
;     for (int n3 = 0; n3 < 3; ++n3) {
;       const bf16_t* X = (const bf16_t*)(p.ws + (n3 == 0 ? O_AQ : (n3 == 1 ? O_BQ : O_CQ)));
;       f32x16 acc[2][2]; zero_acc(acc);
;       gemm_mid(W + ((size_t)n3 * 1024 + nt_ * 128) * 512, 512, X, 512, 1 << 30, 64, 8, mt_ * 256, acc, sm);
; #pragma unroll
;       for (int mt = 0; mt < 2; ++mt) {
;         const int m = mt_ * 256 + wm * 64 + mt * 32 + lr;
; #pragma unroll
;         for (int nt = 0; nt < 2; ++nt)
; #pragma unroll
;           for (int qd = 0; qd < 4; ++qd) {
;             const int n = nt_ * 128 + wn * 64 + nt * 32 + 8 * qd + 4 * lh;
;             typedef unsigned u32x2_t __attribute__((ext_vector_type(2)));
;             const u32x2_t gq_ = __builtin_nontemporal_load((const u32x2_t*)(mgs + ((size_t)((n3 * 1024 + n) >> 2) * T_ + m) * 4));
.LBB0_1090:
	s_and_b32 s0, s7, 0xffffff80
	s_ashr_i32 s1, s0, 31
	s_and_b32 s2, s6, 0x700
	s_add_i32 s8, s8, s10
	s_or_b32 s9, s2, s30
	s_lshl_b64 s[2:3], s[0:1], 10
	s_add_u32 s2, s4, s2
	s_addc_u32 s3, s5, s3
	v_and_b32_e32 v190, 63, v195
	v_lshrrev_b32_e32 v191, 6, v195
	v_and_b32_e32 v98, 31, v190
	v_lshrrev_b32_e32 v99, 5, v190
	v_bfe_u32 v100, v98, 1, 3
	v_lshlrev_b32_e32 v101, 7, v98
	v_xor_b32_e32 v102, v99, v100
	v_lshl_add_u32 v101, v102, 4, v101
	v_and_b32_e32 v102, 1, v191
	v_lshrrev_b32_e32 v103, 1, v191
	v_readfirstlane_b32 s50, v191
	v_lshl_add_u32 v168, v102, 13, v101
	v_lshl_add_u32 v172, v103, 13, v101
	v_add_u32_e32 v172, 0xc000, v172
	v_xor_b32_e32 v169, 0x20, v168
	v_xor_b32_e32 v173, 0x20, v172
	v_xor_b32_e32 v170, 0x40, v168
	v_xor_b32_e32 v174, 0x40, v172
	v_xor_b32_e32 v171, 0x60, v168
	v_xor_b32_e32 v175, 0x60, v172
	v_add_u32_e32 v176, 0x10000, v172
	v_add_u32_e32 v177, 0x10000, v173
	v_add_u32_e32 v178, 0x10000, v174
	v_add_u32_e32 v179, 0x10000, v175
	s_lshl_b32 s51, s50, 12
	s_lshl_b32 s50, s50, 11
	s_add_u32 s51, s51, 0xc000
	v_lshrrev_b32_e32 v104, 3, v190
	v_and_b32_e32 v105, 7, v190
	v_lshrrev_b32_e32 v192, 4, v190
	v_xor_b32_e32 v105, v105, v192
	v_lshlrev_b32_e32 v105, 4, v105
	v_lshl_add_u32 v192, v191, 4, v104
	v_lshl_add_u32 v180, v192, 10, v105
	v_xor_b32_e32 v181, 64, v180
	v_add_u32_e32 v181, 0x2000, v181
	v_lshl_add_u32 v192, v191, 5, v104
	v_lshl_add_u32 v182, v192, 10, v105
	v_xor_b32_e32 v183, 64, v182
	v_add_u32_e32 v183, 0x2000, v183
	v_add_u32_e32 v184, 0x4000, v182
	v_add_u32_e32 v185, 0x4000, v183
	v_lshl_add_u32 v104, v103, 6, v98
	v_add_u32_e32 v104, s9, v104
	v_lshl_add_u32 v105, v102, 4, v99
	s_lshr_b32 s32, s0, 2
	v_add_u32_e32 v105, s32, v105
	v_lshlrev_b32_e32 v105, 17, v105
	v_lshl_add_u32 v186, v104, 3, v105
	v_lshrrev_b32_e32 v104, 3, v190
	v_lshl_add_u32 v104, v103, 6, v104
	v_add_u32_e32 v104, s9, v104
	s_movk_i32 s32, 0x880
	v_mul_lo_u32 v104, v104, s32
	v_and_b32_e32 v105, 7, v190
	v_lshlrev_b32_e32 v105, 4, v105
	v_lshl_add_u32 v105, v102, 7, v105
	s_lshl_b32 s32, s0, 1
	v_add3_u32 v187, v104, v105, s32
	s_movk_i32 s32, 0x2400
	v_mul_lo_u32 v104, v191, s32
	v_mul_u32_u24_e32 v105, 0x90, v98
	v_lshl_add_u32 v105, v99, 3, v105
	v_add_u32_e32 v188, v104, v105
	v_lshrrev_b32_e32 v105, 3, v190
	v_mul_u32_u24_e32 v105, 0x90, v105
	v_add_u32_e32 v105, v104, v105
	v_and_b32_e32 v104, 7, v190
	v_lshl_add_u32 v189, v104, 4, v105
	s_lshl_b32 s32, s9, 10
	s_add_u32 s48, s58, s32
	s_addc_u32 s49, s59, 0
	s_mov_b32 s46, s2
	s_mov_b32 s47, s3
	s_barrier
	s_mov_b32 m0, s50
	s_nop 0
	global_load_lds_dwordx4 v180, s[46:47]
	s_add_u32 m0, s50, 0x400
	s_nop 0
	global_load_lds_dwordx4 v181, s[46:47]
	s_add_u32 s46, s46, 0x80
	s_addc_u32 s47, s47, 0
	s_mov_b32 m0, s51
	s_nop 0
	global_load_lds_dwordx4 v182, s[48:49]
	s_add_u32 m0, s51, 0x400
	s_nop 0
	global_load_lds_dwordx4 v183, s[48:49]
	s_add_u32 m0, s51, 0x800
	s_nop 0
	global_load_lds_dwordx4 v184, s[48:49]
	s_add_u32 m0, s51, 0xc00
	s_nop 0
	global_load_lds_dwordx4 v185, s[48:49]
	s_add_u32 s48, s48, 0x80
	s_addc_u32 s49, s49, 0
	s_add_u32 m0, s50, 0x4000
	s_nop 0
	global_load_lds_dwordx4 v180, s[46:47]
	s_add_u32 m0, s50, 0x4400
	s_nop 0
	global_load_lds_dwordx4 v181, s[46:47]
	s_add_u32 s46, s46, 0x80
	s_addc_u32 s47, s47, 0
	s_add_u32 m0, s51, 0x8000
	s_nop 0
	global_load_lds_dwordx4 v182, s[48:49]
	s_add_u32 m0, s51, 0x8400
	s_nop 0
	global_load_lds_dwordx4 v183, s[48:49]
	s_add_u32 m0, s51, 0x8800
	s_nop 0
	global_load_lds_dwordx4 v184, s[48:49]
	s_add_u32 m0, s51, 0x8c00
	s_nop 0
	global_load_lds_dwordx4 v185, s[48:49]
	s_add_u32 s48, s48, 0x80
	s_addc_u32 s49, s49, 0
	s_add_u32 m0, s50, 0x8000
	s_nop 0
	global_load_lds_dwordx4 v180, s[46:47]
	s_add_u32 m0, s50, 0x8400
	s_nop 0
	global_load_lds_dwordx4 v181, s[46:47]
	s_add_u32 s46, s46, 0x80
	s_addc_u32 s47, s47, 0
	s_add_u32 m0, s51, 0x10000
	s_nop 0
	global_load_lds_dwordx4 v182, s[48:49]
	s_add_u32 m0, s51, 0x10400
	s_nop 0
	global_load_lds_dwordx4 v183, s[48:49]
	s_add_u32 m0, s51, 0x10800
	s_nop 0
	global_load_lds_dwordx4 v184, s[48:49]
	s_add_u32 m0, s51, 0x10c00
	s_nop 0
	global_load_lds_dwordx4 v185, s[48:49]
	s_add_u32 s48, s48, 0x80
	s_addc_u32 s49, s49, 0
	v_add_u32_e32 v190, 0x0, v186
	global_load_dwordx2 v[196:197], v190, s[28:29] nt
	global_load_dwordx2 v[212:213], v190, s[28:29] offset:256 nt
	v_add_u32_e32 v191, 0x40000, v186
	global_load_dwordx2 v[198:199], v191, s[28:29] nt
	global_load_dwordx2 v[214:215], v191, s[28:29] offset:256 nt
	v_add_u32_e32 v190, 0x80000, v186
	global_load_dwordx2 v[200:201], v190, s[28:29] nt
	global_load_dwordx2 v[216:217], v190, s[28:29] offset:256 nt
	v_add_u32_e32 v191, 0xc0000, v186
	global_load_dwordx2 v[202:203], v191, s[28:29] nt
	global_load_dwordx2 v[218:219], v191, s[28:29] offset:256 nt
	v_add_u32_e32 v190, 0x100000, v186
	global_load_dwordx2 v[204:205], v190, s[28:29] nt
	global_load_dwordx2 v[236:237], v190, s[28:29] offset:256 nt
	v_add_u32_e32 v191, 0x140000, v186
	global_load_dwordx2 v[206:207], v191, s[28:29] nt
	global_load_dwordx2 v[238:239], v191, s[28:29] offset:256 nt
	v_add_u32_e32 v190, 0x180000, v186
	global_load_dwordx2 v[208:209], v190, s[28:29] nt
	global_load_dwordx2 v[240:241], v190, s[28:29] offset:256 nt
	v_add_u32_e32 v191, 0x1c0000, v186
	global_load_dwordx2 v[210:211], v191, s[28:29] nt
	global_load_dwordx2 v[242:243], v191, s[28:29] offset:256 nt
	s_waitcnt vmcnt(28)
	s_barrier
; #define MFMA32(a, b, c) __builtin_amdgcn_mfma_f32_32x32x16_bf16((a), (b), (c), 0, 0, 0)
; DI void gemm_mid(const bf16_t* __restrict__ W, int ldw, const bf16_t* __restrict__ X, size_t ldx, int mclamp, int kts,
;                  int nkt, int m0, f32x16 (&acc)[2][2], bf16_t* lds) {
;     ...
;   for (int kt = 0; kt < nkt; ++kt) {
;     const bool more = kt + 1 < nkt;
;     if (more) GM_GLOAD(kt + 1)
;     __builtin_amdgcn_sched_barrier(0);
;     {
;       const bf16_t* wb = lds + (kt & 1) * MID_E + (wn * 64 + lr) * LDT + lh * 8;
;       const bf16_t* xb = lds + (kt & 1) * MID_E + 128 * LDT + (wm * 64 + lr) * LDT + lh * 8;
; #pragma unroll
;       for (int ks = 0; ks < 4; ++ks) {
;         const bf16x8 a0 = *(const bf16x8*)(wb + ks * 16), a1 = *(const bf16x8*)(wb + 32 * LDT + ks * 16);
;         const bf16x8 b0 = *(const bf16x8*)(xb + ks * 16), b1 = *(const bf16x8*)(xb + 32 * LDT + ks * 16);
;         acc[0][0] = MFMA32(a0, b0, acc[0][0]); acc[0][1] = MFMA32(a0, b1, acc[0][1]);
;         acc[1][0] = MFMA32(a1, b0, acc[1][0]); acc[1][1] = MFMA32(a1, b1, acc[1][1]);
;       }
;     }
;     __builtin_amdgcn_sched_barrier(0);
;     if (more) GM_LSTORE((kt + 1) & 1)
;     __syncthreads();
;   }
	ds_read_b128 v[128:131], v172 offset:0
	ds_read_b128 v[120:123], v168 offset:0
	ds_read_b128 v[132:135], v172 offset:4096
	ds_read_b128 v[124:127], v168 offset:4096
	ds_read_b128 v[144:147], v173 offset:0
	ds_read_b128 v[136:139], v169 offset:0
	ds_read_b128 v[148:151], v173 offset:4096
	ds_read_b128 v[140:143], v169 offset:4096
	s_waitcnt lgkmcnt(6)
	v_mfma_f32_32x32x16_bf16 v[0:15], v[120:123], v[128:131], 0
	ds_read_b128 v[160:163], v174 offset:0
	s_waitcnt lgkmcnt(6)
	v_mfma_f32_32x32x16_bf16 v[16:31], v[120:123], v[132:135], 0
	ds_read_b128 v[152:155], v170 offset:0
	s_waitcnt lgkmcnt(6)
	v_mfma_f32_32x32x16_bf16 v[32:47], v[124:127], v[128:131], 0
	ds_read_b128 v[164:167], v174 offset:4096
	v_mfma_f32_32x32x16_bf16 v[48:63], v[124:127], v[132:135], 0
	ds_read_b128 v[156:159], v170 offset:4096
	ds_read_b128 v[128:131], v175 offset:0
	ds_read_b128 v[120:123], v171 offset:0
	ds_read_b128 v[132:135], v175 offset:4096
	ds_read_b128 v[124:127], v171 offset:4096
	s_waitcnt lgkmcnt(10)
	v_mfma_f32_32x32x16_bf16 v[0:15], v[136:139], v[144:147], v[0:15]
	s_waitcnt lgkmcnt(9)
	v_mfma_f32_32x32x16_bf16 v[16:31], v[136:139], v[148:151], v[16:31]
	s_waitcnt lgkmcnt(8)
	v_mfma_f32_32x32x16_bf16 v[32:47], v[140:143], v[144:147], v[32:47]
	v_mfma_f32_32x32x16_bf16 v[48:63], v[140:143], v[148:151], v[48:63]
	s_waitcnt vmcnt(22) lgkmcnt(0)
	s_barrier
	v_mfma_f32_32x32x16_bf16 v[0:15], v[152:155], v[160:163], v[0:15]
	ds_read_b128 v[144:147], v172 offset:32768
	v_mfma_f32_32x32x16_bf16 v[16:31], v[152:155], v[164:167], v[16:31]
	ds_read_b128 v[136:139], v168 offset:16384
	s_mov_b32 m0, s50
	s_nop 0
	global_load_lds_dwordx4 v180, s[46:47]
	v_mfma_f32_32x32x16_bf16 v[32:47], v[156:159], v[160:163], v[32:47]
	ds_read_b128 v[148:151], v172 offset:36864
	v_mfma_f32_32x32x16_bf16 v[48:63], v[156:159], v[164:167], v[48:63]
	ds_read_b128 v[140:143], v168 offset:20480
	s_add_u32 m0, s50, 0x400
	s_nop 0
	global_load_lds_dwordx4 v181, s[46:47]
	s_add_u32 s46, s46, 0x80
	s_addc_u32 s47, s47, 0
	v_mfma_f32_32x32x16_bf16 v[0:15], v[120:123], v[128:131], v[0:15]
	ds_read_b128 v[160:163], v173 offset:32768
	v_mfma_f32_32x32x16_bf16 v[16:31], v[120:123], v[132:135], v[16:31]
	ds_read_b128 v[152:155], v169 offset:16384
	s_mov_b32 m0, s51
	s_nop 0
	global_load_lds_dwordx4 v182, s[48:49]
	v_mfma_f32_32x32x16_bf16 v[32:47], v[124:127], v[128:131], v[32:47]
	ds_read_b128 v[164:167], v173 offset:36864
	v_mfma_f32_32x32x16_bf16 v[48:63], v[124:127], v[132:135], v[48:63]
	ds_read_b128 v[156:159], v169 offset:20480
	s_add_u32 m0, s51, 0x400
	s_nop 0
	global_load_lds_dwordx4 v183, s[48:49]
	s_waitcnt lgkmcnt(6)
	v_mfma_f32_32x32x16_bf16 v[0:15], v[136:139], v[144:147], v[0:15]
	ds_read_b128 v[128:131], v174 offset:32768
	s_waitcnt lgkmcnt(6)
	v_mfma_f32_32x32x16_bf16 v[16:31], v[136:139], v[148:151], v[16:31]
	ds_read_b128 v[120:123], v170 offset:16384
	s_add_u32 m0, s51, 0x800
	s_nop 0
	global_load_lds_dwordx4 v184, s[48:49]
	s_waitcnt lgkmcnt(6)
	v_mfma_f32_32x32x16_bf16 v[32:47], v[140:143], v[144:147], v[32:47]
	ds_read_b128 v[132:135], v174 offset:36864
	v_mfma_f32_32x32x16_bf16 v[48:63], v[140:143], v[148:151], v[48:63]
	ds_read_b128 v[124:127], v170 offset:20480
	s_add_u32 m0, s51, 0xc00
	s_nop 0
	global_load_lds_dwordx4 v185, s[48:49]
	s_add_u32 s48, s48, 0x80
	s_addc_u32 s49, s49, 0
	ds_read_b128 v[144:147], v175 offset:32768
	ds_read_b128 v[136:139], v171 offset:16384
	ds_read_b128 v[148:151], v175 offset:36864
	ds_read_b128 v[140:143], v171 offset:20480
	s_waitcnt lgkmcnt(10)
	v_mfma_f32_32x32x16_bf16 v[0:15], v[152:155], v[160:163], v[0:15]
	s_waitcnt lgkmcnt(9)
	v_mfma_f32_32x32x16_bf16 v[16:31], v[152:155], v[164:167], v[16:31]
	s_waitcnt lgkmcnt(8)
	v_mfma_f32_32x32x16_bf16 v[32:47], v[156:159], v[160:163], v[32:47]
	v_mfma_f32_32x32x16_bf16 v[48:63], v[156:159], v[164:167], v[48:63]
	s_waitcnt vmcnt(22) lgkmcnt(0)
	s_barrier
	v_mfma_f32_32x32x16_bf16 v[0:15], v[120:123], v[128:131], v[0:15]
	ds_read_b128 v[160:163], v176 offset:0
	v_mfma_f32_32x32x16_bf16 v[16:31], v[120:123], v[132:135], v[16:31]
	ds_read_b128 v[152:155], v168 offset:32768
	s_add_u32 m0, s50, 0x4000
	s_nop 0
	global_load_lds_dwordx4 v180, s[46:47]
	v_mfma_f32_32x32x16_bf16 v[32:47], v[124:127], v[128:131], v[32:47]
	ds_read_b128 v[164:167], v176 offset:4096
	v_mfma_f32_32x32x16_bf16 v[48:63], v[124:127], v[132:135], v[48:63]
	ds_read_b128 v[156:159], v168 offset:36864
	s_add_u32 m0, s50, 0x4400
	s_nop 0
	global_load_lds_dwordx4 v181, s[46:47]
	s_add_u32 s46, s46, 0x80
	s_addc_u32 s47, s47, 0
	v_mfma_f32_32x32x16_bf16 v[0:15], v[136:139], v[144:147], v[0:15]
	ds_read_b128 v[128:131], v177 offset:0
	v_mfma_f32_32x32x16_bf16 v[16:31], v[136:139], v[148:151], v[16:31]
	ds_read_b128 v[120:123], v169 offset:32768
	s_add_u32 m0, s51, 0x8000
	s_nop 0
	global_load_lds_dwordx4 v182, s[48:49]
	v_mfma_f32_32x32x16_bf16 v[32:47], v[140:143], v[144:147], v[32:47]
	ds_read_b128 v[132:135], v177 offset:4096
	v_mfma_f32_32x32x16_bf16 v[48:63], v[140:143], v[148:151], v[48:63]
	ds_read_b128 v[124:127], v169 offset:36864
	s_add_u32 m0, s51, 0x8400
	s_nop 0
	global_load_lds_dwordx4 v183, s[48:49]
	s_waitcnt lgkmcnt(6)
	v_mfma_f32_32x32x16_bf16 v[0:15], v[152:155], v[160:163], v[0:15]
	ds_read_b128 v[144:147], v178 offset:0
	s_waitcnt lgkmcnt(6)
	v_mfma_f32_32x32x16_bf16 v[16:31], v[152:155], v[164:167], v[16:31]
	ds_read_b128 v[136:139], v170 offset:32768
	s_add_u32 m0, s51, 0x8800
	s_nop 0
	global_load_lds_dwordx4 v184, s[48:49]
	s_waitcnt lgkmcnt(6)
	v_mfma_f32_32x32x16_bf16 v[32:47], v[156:159], v[160:163], v[32:47]
	ds_read_b128 v[148:151], v178 offset:4096
	v_mfma_f32_32x32x16_bf16 v[48:63], v[156:159], v[164:167], v[48:63]
	ds_read_b128 v[140:143], v170 offset:36864
	s_add_u32 m0, s51, 0x8c00
	s_nop 0
	global_load_lds_dwordx4 v185, s[48:49]
	s_add_u32 s48, s48, 0x80
	s_addc_u32 s49, s49, 0
	ds_read_b128 v[160:163], v179 offset:0
	ds_read_b128 v[152:155], v171 offset:32768
	ds_read_b128 v[164:167], v179 offset:4096
	ds_read_b128 v[156:159], v171 offset:36864
	s_waitcnt lgkmcnt(10)
	v_mfma_f32_32x32x16_bf16 v[0:15], v[120:123], v[128:131], v[0:15]
	s_waitcnt lgkmcnt(9)
	v_mfma_f32_32x32x16_bf16 v[16:31], v[120:123], v[132:135], v[16:31]
	s_waitcnt lgkmcnt(8)
	v_mfma_f32_32x32x16_bf16 v[32:47], v[124:127], v[128:131], v[32:47]
	v_mfma_f32_32x32x16_bf16 v[48:63], v[124:127], v[132:135], v[48:63]
	s_waitcnt vmcnt(6) lgkmcnt(0)
	s_barrier
; #define MFMA32(a, b, c) __builtin_amdgcn_mfma_f32_32x32x16_bf16((a), (b), (c), 0, 0, 0)
; DI void gemm_mid(const bf16_t* __restrict__ W, int ldw, const bf16_t* __restrict__ X, size_t ldx, int mclamp, int kts,
;                  int nkt, int m0, f32x16 (&acc)[2][2], bf16_t* lds) {
;     ...
;   for (int kt = 0; kt < nkt; ++kt) {
;     const bool more = kt + 1 < nkt;
;     if (more) GM_GLOAD(kt + 1)
;     __builtin_amdgcn_sched_barrier(0);
;     {
;       const bf16_t* wb = lds + (kt & 1) * MID_E + (wn * 64 + lr) * LDT + lh * 8;
;       const bf16_t* xb = lds + (kt & 1) * MID_E + 128 * LDT + (wm * 64 + lr) * LDT + lh * 8;
; #pragma unroll
;       for (int ks = 0; ks < 4; ++ks) {
;         const bf16x8 a0 = *(const bf16x8*)(wb + ks * 16), a1 = *(const bf16x8*)(wb + 32 * LDT + ks * 16);
;         const bf16x8 b0 = *(const bf16x8*)(xb + ks * 16), b1 = *(const bf16x8*)(xb + 32 * LDT + ks * 16);
;         acc[0][0] = MFMA32(a0, b0, acc[0][0]); acc[0][1] = MFMA32(a0, b1, acc[0][1]);
;         acc[1][0] = MFMA32(a1, b0, acc[1][0]); acc[1][1] = MFMA32(a1, b1, acc[1][1]);
;       }
;     }
;     __builtin_amdgcn_sched_barrier(0);
;     if (more) GM_LSTORE((kt + 1) & 1)
;     __syncthreads();
;   }
	v_mfma_f32_32x32x16_bf16 v[0:15], v[136:139], v[144:147], v[0:15]
	ds_read_b128 v[128:131], v172 offset:0
	v_mfma_f32_32x32x16_bf16 v[16:31], v[136:139], v[148:151], v[16:31]
	ds_read_b128 v[120:123], v168 offset:0
	s_add_u32 m0, s50, 0x8000
	s_nop 0
	global_load_lds_dwordx4 v180, s[46:47]
	v_mfma_f32_32x32x16_bf16 v[32:47], v[140:143], v[144:147], v[32:47]
	ds_read_b128 v[132:135], v172 offset:4096
	v_mfma_f32_32x32x16_bf16 v[48:63], v[140:143], v[148:151], v[48:63]
	ds_read_b128 v[124:127], v168 offset:4096
	s_add_u32 m0, s50, 0x8400
	s_nop 0
	global_load_lds_dwordx4 v181, s[46:47]
	s_add_u32 s46, s46, 0x80
	s_addc_u32 s47, s47, 0
	v_mfma_f32_32x32x16_bf16 v[0:15], v[152:155], v[160:163], v[0:15]
	ds_read_b128 v[144:147], v173 offset:0
	v_mfma_f32_32x32x16_bf16 v[16:31], v[152:155], v[164:167], v[16:31]
	ds_read_b128 v[136:139], v169 offset:0
	s_add_u32 m0, s51, 0x10000
	s_nop 0
	global_load_lds_dwordx4 v182, s[48:49]
	v_mfma_f32_32x32x16_bf16 v[32:47], v[156:159], v[160:163], v[32:47]
	ds_read_b128 v[148:151], v173 offset:4096
	v_mfma_f32_32x32x16_bf16 v[48:63], v[156:159], v[164:167], v[48:63]
	ds_read_b128 v[140:143], v169 offset:4096
	s_add_u32 m0, s51, 0x10400
	s_nop 0
	global_load_lds_dwordx4 v183, s[48:49]
	s_waitcnt lgkmcnt(6)
	v_mfma_f32_32x32x16_bf16 v[0:15], v[120:123], v[128:131], v[0:15]
	ds_read_b128 v[160:163], v174 offset:0
	s_waitcnt lgkmcnt(6)
	v_mfma_f32_32x32x16_bf16 v[16:31], v[120:123], v[132:135], v[16:31]
	ds_read_b128 v[152:155], v170 offset:0
	s_add_u32 m0, s51, 0x10800
	s_nop 0
	global_load_lds_dwordx4 v184, s[48:49]
	s_waitcnt lgkmcnt(6)
	v_mfma_f32_32x32x16_bf16 v[32:47], v[124:127], v[128:131], v[32:47]
	ds_read_b128 v[164:167], v174 offset:4096
	v_mfma_f32_32x32x16_bf16 v[48:63], v[124:127], v[132:135], v[48:63]
	ds_read_b128 v[156:159], v170 offset:4096
	s_add_u32 m0, s51, 0x10c00
	s_nop 0
	global_load_lds_dwordx4 v185, s[48:49]
	s_add_u32 s48, s48, 0x80
	s_addc_u32 s49, s49, 0
	ds_read_b128 v[128:131], v175 offset:0
	ds_read_b128 v[120:123], v171 offset:0
	ds_read_b128 v[132:135], v175 offset:4096
	ds_read_b128 v[124:127], v171 offset:4096
	s_waitcnt lgkmcnt(10)
	v_mfma_f32_32x32x16_bf16 v[0:15], v[136:139], v[144:147], v[0:15]
	s_waitcnt lgkmcnt(9)
	v_mfma_f32_32x32x16_bf16 v[16:31], v[136:139], v[148:151], v[16:31]
	s_waitcnt lgkmcnt(8)
	v_mfma_f32_32x32x16_bf16 v[32:47], v[140:143], v[144:147], v[32:47]
	v_mfma_f32_32x32x16_bf16 v[48:63], v[140:143], v[148:151], v[48:63]
	s_waitcnt vmcnt(6) lgkmcnt(0)
	s_barrier
	v_mfma_f32_32x32x16_bf16 v[0:15], v[152:155], v[160:163], v[0:15]
	ds_read_b128 v[144:147], v172 offset:32768
	v_mfma_f32_32x32x16_bf16 v[16:31], v[152:155], v[164:167], v[16:31]
	ds_read_b128 v[136:139], v168 offset:16384
	s_mov_b32 m0, s50
	s_nop 0
	global_load_lds_dwordx4 v180, s[46:47]
	v_mfma_f32_32x32x16_bf16 v[32:47], v[156:159], v[160:163], v[32:47]
	ds_read_b128 v[148:151], v172 offset:36864
	v_mfma_f32_32x32x16_bf16 v[48:63], v[156:159], v[164:167], v[48:63]
	ds_read_b128 v[140:143], v168 offset:20480
	s_add_u32 m0, s50, 0x400
	s_nop 0
	global_load_lds_dwordx4 v181, s[46:47]
	s_add_u32 s46, s46, 0x80
	s_addc_u32 s47, s47, 0
	v_mfma_f32_32x32x16_bf16 v[0:15], v[120:123], v[128:131], v[0:15]
	ds_read_b128 v[160:163], v173 offset:32768
	v_mfma_f32_32x32x16_bf16 v[16:31], v[120:123], v[132:135], v[16:31]
	ds_read_b128 v[152:155], v169 offset:16384
	s_mov_b32 m0, s51
	s_nop 0
	global_load_lds_dwordx4 v182, s[48:49]
	v_mfma_f32_32x32x16_bf16 v[32:47], v[124:127], v[128:131], v[32:47]
	ds_read_b128 v[164:167], v173 offset:36864
	v_mfma_f32_32x32x16_bf16 v[48:63], v[124:127], v[132:135], v[48:63]
	ds_read_b128 v[156:159], v169 offset:20480
	s_add_u32 m0, s51, 0x400
	s_nop 0
	global_load_lds_dwordx4 v183, s[48:49]
	s_waitcnt lgkmcnt(6)
	v_mfma_f32_32x32x16_bf16 v[0:15], v[136:139], v[144:147], v[0:15]
	ds_read_b128 v[128:131], v174 offset:32768
	s_waitcnt lgkmcnt(6)
	v_mfma_f32_32x32x16_bf16 v[16:31], v[136:139], v[148:151], v[16:31]
	ds_read_b128 v[120:123], v170 offset:16384
	s_add_u32 m0, s51, 0x800
	s_nop 0
	global_load_lds_dwordx4 v184, s[48:49]
	s_waitcnt lgkmcnt(6)
	v_mfma_f32_32x32x16_bf16 v[32:47], v[140:143], v[144:147], v[32:47]
	ds_read_b128 v[132:135], v174 offset:36864
	v_mfma_f32_32x32x16_bf16 v[48:63], v[140:143], v[148:151], v[48:63]
	ds_read_b128 v[124:127], v170 offset:20480
	s_add_u32 m0, s51, 0xc00
	s_nop 0
	global_load_lds_dwordx4 v185, s[48:49]
	s_add_u32 s48, s48, 0x80
	s_addc_u32 s49, s49, 0
	ds_read_b128 v[144:147], v175 offset:32768
	ds_read_b128 v[136:139], v171 offset:16384
	ds_read_b128 v[148:151], v175 offset:36864
	ds_read_b128 v[140:143], v171 offset:20480
	s_waitcnt lgkmcnt(10)
	v_mfma_f32_32x32x16_bf16 v[0:15], v[152:155], v[160:163], v[0:15]
	s_waitcnt lgkmcnt(9)
	v_mfma_f32_32x32x16_bf16 v[16:31], v[152:155], v[164:167], v[16:31]
	s_waitcnt lgkmcnt(8)
	v_mfma_f32_32x32x16_bf16 v[32:47], v[156:159], v[160:163], v[32:47]
	v_mfma_f32_32x32x16_bf16 v[48:63], v[156:159], v[164:167], v[48:63]
	s_waitcnt vmcnt(6) lgkmcnt(0)
	s_barrier
; #define MFMA32(a, b, c) __builtin_amdgcn_mfma_f32_32x32x16_bf16((a), (b), (c), 0, 0, 0)
; DI void gemm_mid(const bf16_t* __restrict__ W, int ldw, const bf16_t* __restrict__ X, size_t ldx, int mclamp, int kts,
;                  int nkt, int m0, f32x16 (&acc)[2][2], bf16_t* lds) {
;     ...
;   for (int kt = 0; kt < nkt; ++kt) {
;     const bool more = kt + 1 < nkt;
;     if (more) GM_GLOAD(kt + 1)
;     __builtin_amdgcn_sched_barrier(0);
;     {
;       const bf16_t* wb = lds + (kt & 1) * MID_E + (wn * 64 + lr) * LDT + lh * 8;
;       const bf16_t* xb = lds + (kt & 1) * MID_E + 128 * LDT + (wm * 64 + lr) * LDT + lh * 8;
; #pragma unroll
;       for (int ks = 0; ks < 4; ++ks) {
;         const bf16x8 a0 = *(const bf16x8*)(wb + ks * 16), a1 = *(const bf16x8*)(wb + 32 * LDT + ks * 16);
;         const bf16x8 b0 = *(const bf16x8*)(xb + ks * 16), b1 = *(const bf16x8*)(xb + 32 * LDT + ks * 16);
;         acc[0][0] = MFMA32(a0, b0, acc[0][0]); acc[0][1] = MFMA32(a0, b1, acc[0][1]);
;         acc[1][0] = MFMA32(a1, b0, acc[1][0]); acc[1][1] = MFMA32(a1, b1, acc[1][1]);
;       }
;     }
;     __builtin_amdgcn_sched_barrier(0);
;     if (more) GM_LSTORE((kt + 1) & 1)
;     __syncthreads();
;   }
	v_mfma_f32_32x32x16_bf16 v[0:15], v[120:123], v[128:131], v[0:15]
	ds_read_b128 v[160:163], v176 offset:0
	v_mfma_f32_32x32x16_bf16 v[16:31], v[120:123], v[132:135], v[16:31]
	ds_read_b128 v[152:155], v168 offset:32768
	s_add_u32 m0, s50, 0x4000
	s_nop 0
	global_load_lds_dwordx4 v180, s[46:47]
	v_mfma_f32_32x32x16_bf16 v[32:47], v[124:127], v[128:131], v[32:47]
	ds_read_b128 v[164:167], v176 offset:4096
	v_mfma_f32_32x32x16_bf16 v[48:63], v[124:127], v[132:135], v[48:63]
	ds_read_b128 v[156:159], v168 offset:36864
	s_add_u32 m0, s50, 0x4400
	s_nop 0
	global_load_lds_dwordx4 v181, s[46:47]
	s_add_u32 s46, s46, 0x80
	s_addc_u32 s47, s47, 0
	v_mfma_f32_32x32x16_bf16 v[0:15], v[136:139], v[144:147], v[0:15]
	ds_read_b128 v[128:131], v177 offset:0
	v_mfma_f32_32x32x16_bf16 v[16:31], v[136:139], v[148:151], v[16:31]
	ds_read_b128 v[120:123], v169 offset:32768
	s_add_u32 m0, s51, 0x8000
	s_nop 0
	global_load_lds_dwordx4 v182, s[48:49]
	v_mfma_f32_32x32x16_bf16 v[32:47], v[140:143], v[144:147], v[32:47]
	ds_read_b128 v[132:135], v177 offset:4096
	v_mfma_f32_32x32x16_bf16 v[48:63], v[140:143], v[148:151], v[48:63]
	ds_read_b128 v[124:127], v169 offset:36864
	s_add_u32 m0, s51, 0x8400
	s_nop 0
	global_load_lds_dwordx4 v183, s[48:49]
	s_waitcnt lgkmcnt(6)
	v_mfma_f32_32x32x16_bf16 v[0:15], v[152:155], v[160:163], v[0:15]
	ds_read_b128 v[144:147], v178 offset:0
	s_waitcnt lgkmcnt(6)
	v_mfma_f32_32x32x16_bf16 v[16:31], v[152:155], v[164:167], v[16:31]
	ds_read_b128 v[136:139], v170 offset:32768
	s_add_u32 m0, s51, 0x8800
	s_nop 0
	global_load_lds_dwordx4 v184, s[48:49]
	s_waitcnt lgkmcnt(6)
	v_mfma_f32_32x32x16_bf16 v[32:47], v[156:159], v[160:163], v[32:47]
	ds_read_b128 v[148:151], v178 offset:4096
	v_mfma_f32_32x32x16_bf16 v[48:63], v[156:159], v[164:167], v[48:63]
	ds_read_b128 v[140:143], v170 offset:36864
	s_add_u32 m0, s51, 0x8c00
	s_nop 0
	global_load_lds_dwordx4 v185, s[48:49]
	s_add_u32 s48, s48, 0x80
	s_addc_u32 s49, s49, 0
	ds_read_b128 v[160:163], v179 offset:0
	ds_read_b128 v[152:155], v171 offset:32768
	ds_read_b128 v[164:167], v179 offset:4096
	ds_read_b128 v[156:159], v171 offset:36864
	s_waitcnt lgkmcnt(10)
	v_mfma_f32_32x32x16_bf16 v[0:15], v[120:123], v[128:131], v[0:15]
	s_waitcnt lgkmcnt(9)
	v_mfma_f32_32x32x16_bf16 v[16:31], v[120:123], v[132:135], v[16:31]
	s_waitcnt lgkmcnt(8)
	v_mfma_f32_32x32x16_bf16 v[32:47], v[124:127], v[128:131], v[32:47]
	v_mfma_f32_32x32x16_bf16 v[48:63], v[124:127], v[132:135], v[48:63]
	s_waitcnt vmcnt(6) lgkmcnt(0)
	s_barrier
	v_mfma_f32_32x32x16_bf16 v[0:15], v[136:139], v[144:147], v[0:15]
	ds_read_b128 v[128:131], v172 offset:0
	v_mfma_f32_32x32x16_bf16 v[16:31], v[136:139], v[148:151], v[16:31]
	ds_read_b128 v[120:123], v168 offset:0
	v_mfma_f32_32x32x16_bf16 v[32:47], v[140:143], v[144:147], v[32:47]
	ds_read_b128 v[132:135], v172 offset:4096
	v_mfma_f32_32x32x16_bf16 v[48:63], v[140:143], v[148:151], v[48:63]
	ds_read_b128 v[124:127], v168 offset:4096
	v_mfma_f32_32x32x16_bf16 v[0:15], v[152:155], v[160:163], v[0:15]
	ds_read_b128 v[144:147], v173 offset:0
	v_mfma_f32_32x32x16_bf16 v[16:31], v[152:155], v[164:167], v[16:31]
	ds_read_b128 v[136:139], v169 offset:0
	v_mfma_f32_32x32x16_bf16 v[32:47], v[156:159], v[160:163], v[32:47]
	ds_read_b128 v[148:151], v173 offset:4096
	v_mfma_f32_32x32x16_bf16 v[48:63], v[156:159], v[164:167], v[48:63]
	ds_read_b128 v[140:143], v169 offset:4096
	s_waitcnt lgkmcnt(6)
	v_mfma_f32_32x32x16_bf16 v[0:15], v[120:123], v[128:131], v[0:15]
	ds_read_b128 v[160:163], v174 offset:0
	s_waitcnt lgkmcnt(6)
	v_mfma_f32_32x32x16_bf16 v[16:31], v[120:123], v[132:135], v[16:31]
	ds_read_b128 v[152:155], v170 offset:0
	s_waitcnt lgkmcnt(6)
	v_mfma_f32_32x32x16_bf16 v[32:47], v[124:127], v[128:131], v[32:47]
	ds_read_b128 v[164:167], v174 offset:4096
	v_mfma_f32_32x32x16_bf16 v[48:63], v[124:127], v[132:135], v[48:63]
	ds_read_b128 v[156:159], v170 offset:4096
	ds_read_b128 v[128:131], v175 offset:0
	ds_read_b128 v[120:123], v171 offset:0
	ds_read_b128 v[132:135], v175 offset:4096
	ds_read_b128 v[124:127], v171 offset:4096
	s_waitcnt lgkmcnt(10)
	v_mfma_f32_32x32x16_bf16 v[0:15], v[136:139], v[144:147], v[0:15]
	s_waitcnt lgkmcnt(9)
	v_mfma_f32_32x32x16_bf16 v[16:31], v[136:139], v[148:151], v[16:31]
	s_waitcnt lgkmcnt(8)
	v_mfma_f32_32x32x16_bf16 v[32:47], v[140:143], v[144:147], v[32:47]
	v_mfma_f32_32x32x16_bf16 v[48:63], v[140:143], v[148:151], v[48:63]
	s_waitcnt vmcnt(0) lgkmcnt(0)
	s_barrier
	v_mfma_f32_32x32x16_bf16 v[0:15], v[152:155], v[160:163], v[0:15]
	ds_read_b128 v[144:147], v172 offset:32768
	v_mfma_f32_32x32x16_bf16 v[16:31], v[152:155], v[164:167], v[16:31]
	ds_read_b128 v[136:139], v168 offset:16384
	v_mfma_f32_32x32x16_bf16 v[32:47], v[156:159], v[160:163], v[32:47]
	ds_read_b128 v[148:151], v172 offset:36864
	v_mfma_f32_32x32x16_bf16 v[48:63], v[156:159], v[164:167], v[48:63]
	ds_read_b128 v[140:143], v168 offset:20480
	v_mfma_f32_32x32x16_bf16 v[0:15], v[120:123], v[128:131], v[0:15]
	ds_read_b128 v[160:163], v173 offset:32768
	v_mfma_f32_32x32x16_bf16 v[16:31], v[120:123], v[132:135], v[16:31]
	ds_read_b128 v[152:155], v169 offset:16384
	v_mfma_f32_32x32x16_bf16 v[32:47], v[124:127], v[128:131], v[32:47]
	ds_read_b128 v[164:167], v173 offset:36864
	v_mfma_f32_32x32x16_bf16 v[48:63], v[124:127], v[132:135], v[48:63]
	ds_read_b128 v[156:159], v169 offset:20480
	s_waitcnt lgkmcnt(6)
	v_mfma_f32_32x32x16_bf16 v[0:15], v[136:139], v[144:147], v[0:15]
	ds_read_b128 v[128:131], v174 offset:32768
	s_waitcnt lgkmcnt(6)
	v_mfma_f32_32x32x16_bf16 v[16:31], v[136:139], v[148:151], v[16:31]
	ds_read_b128 v[120:123], v170 offset:16384
	s_waitcnt lgkmcnt(6)
	v_mfma_f32_32x32x16_bf16 v[32:47], v[140:143], v[144:147], v[32:47]
	ds_read_b128 v[132:135], v174 offset:36864
	v_mfma_f32_32x32x16_bf16 v[48:63], v[140:143], v[148:151], v[48:63]
	ds_read_b128 v[124:127], v170 offset:20480
	ds_read_b128 v[144:147], v175 offset:32768
	ds_read_b128 v[136:139], v171 offset:16384
	ds_read_b128 v[148:151], v175 offset:36864
	ds_read_b128 v[140:143], v171 offset:20480
	s_waitcnt lgkmcnt(10)
	v_mfma_f32_32x32x16_bf16 v[0:15], v[152:155], v[160:163], v[0:15]
	s_waitcnt lgkmcnt(9)
	v_mfma_f32_32x32x16_bf16 v[16:31], v[152:155], v[164:167], v[16:31]
	s_waitcnt lgkmcnt(8)
	v_mfma_f32_32x32x16_bf16 v[32:47], v[156:159], v[160:163], v[32:47]
	v_mfma_f32_32x32x16_bf16 v[48:63], v[156:159], v[164:167], v[48:63]
	s_waitcnt lgkmcnt(0)
	s_barrier
; #define MFMA32(a, b, c) __builtin_amdgcn_mfma_f32_32x32x16_bf16((a), (b), (c), 0, 0, 0)
; DI float bf2f(bf16_t b) { return __uint_as_float(((unsigned)b) << 16); }
; DI unsigned pack2(float a, float b) { f32x2_t v = {a, b}; bf16x2_t r = __builtin_convertvector(v, bf16x2_t); return __builtin_bit_cast(unsigned, r); }
; DI void gemm_mid(const bf16_t* __restrict__ W, int ldw, const bf16_t* __restrict__ X, size_t ldx, int mclamp, int kts,
;                  int nkt, int m0, f32x16 (&acc)[2][2], bf16_t* lds) {
;     ...
;       for (int ks = 0; ks < 4; ++ks) {
;         const bf16x8 a0 = *(const bf16x8*)(wb + ks * 16), a1 = *(const bf16x8*)(wb + 32 * LDT + ks * 16);
;         const bf16x8 b0 = *(const bf16x8*)(xb + ks * 16), b1 = *(const bf16x8*)(xb + 32 * LDT + ks * 16);
;         acc[0][0] = MFMA32(a0, b0, acc[0][0]); acc[0][1] = MFMA32(a0, b1, acc[0][1]);
;         acc[1][0] = MFMA32(a1, b0, acc[1][0]); acc[1][1] = MFMA32(a1, b1, acc[1][1]);
;       }
; DI void phase_merge(const P& p, int layer, bf16_t* sm, const Geo& ge) {
;     ...
; #pragma unroll
;       for (int mt = 0; mt < 2; ++mt) {
;         const int m = mt_ * 256 + wm * 64 + mt * 32 + lr;
; #pragma unroll
;         for (int nt = 0; nt < 2; ++nt)
; #pragma unroll
;           for (int qd = 0; qd < 4; ++qd) {
;             const int n = nt_ * 128 + wn * 64 + nt * 32 + 8 * qd + 4 * lh;
;             typedef unsigned u32x2_t __attribute__((ext_vector_type(2)));
;             const u32x2_t gq_ = __builtin_nontemporal_load((const u32x2_t*)(mgs + ((size_t)((n3 * 1024 + n) >> 2) * T_ + m) * 4));
;             const uint2 gq = make_uint2(gq_[0], gq_[1]);
;             const unsigned z01 = zp[nt][mt][2 * qd], z23 = zp[nt][mt][2 * qd + 1];
;             const float v0 = bf2f((bf16_t)(z01 & 0xffff)) + bf2f((bf16_t)(gq.x & 0xffff)) * acc[nt][mt][4 * qd];
;             const float v1 = bf2f((bf16_t)(z01 >> 16)) + bf2f((bf16_t)(gq.x >> 16)) * acc[nt][mt][4 * qd + 1];
;             const float v2 = bf2f((bf16_t)(z23 & 0xffff)) + bf2f((bf16_t)(gq.y & 0xffff)) * acc[nt][mt][4 * qd + 2];
;             const float v3 = bf2f((bf16_t)(z23 >> 16)) + bf2f((bf16_t)(gq.y >> 16)) * acc[nt][mt][4 * qd + 3];
;             zp[nt][mt][2 * qd] = pack2(v0, v1);
;             zp[nt][mt][2 * qd + 1] = pack2(v2, v3);
;           }
	v_mfma_f32_32x32x16_bf16 v[0:15], v[120:123], v[128:131], v[0:15]
	v_mfma_f32_32x32x16_bf16 v[16:31], v[120:123], v[132:135], v[16:31]
	v_mfma_f32_32x32x16_bf16 v[32:47], v[124:127], v[128:131], v[32:47]
	v_mfma_f32_32x32x16_bf16 v[48:63], v[124:127], v[132:135], v[48:63]
	v_mfma_f32_32x32x16_bf16 v[0:15], v[136:139], v[144:147], v[0:15]
	v_mfma_f32_32x32x16_bf16 v[16:31], v[136:139], v[148:151], v[16:31]
	v_mfma_f32_32x32x16_bf16 v[32:47], v[140:143], v[144:147], v[32:47]
	v_mfma_f32_32x32x16_bf16 v[48:63], v[140:143], v[148:151], v[48:63]
	s_add_u32 s46, s46, 0xffc00
	s_addc_u32 s47, s47, 0
	s_add_u32 s48, s48, 0xfffc00
	s_addc_u32 s49, s49, 0
	s_mov_b32 m0, s50
	s_nop 0
	global_load_lds_dwordx4 v180, s[46:47]
	s_add_u32 m0, s50, 0x400
	s_nop 0
	global_load_lds_dwordx4 v181, s[46:47]
	s_add_u32 s46, s46, 0x80
	s_addc_u32 s47, s47, 0
	s_mov_b32 m0, s51
	s_nop 0
	global_load_lds_dwordx4 v182, s[48:49]
	s_add_u32 m0, s51, 0x400
	s_nop 0
	global_load_lds_dwordx4 v183, s[48:49]
	s_add_u32 m0, s51, 0x800
	s_nop 0
	global_load_lds_dwordx4 v184, s[48:49]
	s_add_u32 m0, s51, 0xc00
	s_nop 0
	global_load_lds_dwordx4 v185, s[48:49]
	s_add_u32 s48, s48, 0x80
	s_addc_u32 s49, s49, 0
	s_add_u32 m0, s50, 0x4000
	s_nop 0
	global_load_lds_dwordx4 v180, s[46:47]
	s_add_u32 m0, s50, 0x4400
	s_nop 0
	global_load_lds_dwordx4 v181, s[46:47]
	s_add_u32 s46, s46, 0x80
	s_addc_u32 s47, s47, 0
	s_add_u32 m0, s51, 0x8000
	s_nop 0
	global_load_lds_dwordx4 v182, s[48:49]
	s_add_u32 m0, s51, 0x8400
	s_nop 0
	global_load_lds_dwordx4 v183, s[48:49]
	s_add_u32 m0, s51, 0x8800
	s_nop 0
	global_load_lds_dwordx4 v184, s[48:49]
	s_add_u32 m0, s51, 0x8c00
	s_nop 0
	global_load_lds_dwordx4 v185, s[48:49]
	s_add_u32 s48, s48, 0x80
	s_addc_u32 s49, s49, 0
	s_add_u32 m0, s50, 0x8000
	s_nop 0
	global_load_lds_dwordx4 v180, s[46:47]
	s_add_u32 m0, s50, 0x8400
	s_nop 0
	global_load_lds_dwordx4 v181, s[46:47]
	s_add_u32 s46, s46, 0x80
	s_addc_u32 s47, s47, 0
	s_add_u32 m0, s51, 0x10000
	s_nop 0
	global_load_lds_dwordx4 v182, s[48:49]
	s_add_u32 m0, s51, 0x10400
	s_nop 0
	global_load_lds_dwordx4 v183, s[48:49]
	s_add_u32 m0, s51, 0x10800
	s_nop 0
	global_load_lds_dwordx4 v184, s[48:49]
	s_add_u32 m0, s51, 0x10c00
	s_nop 0
	global_load_lds_dwordx4 v185, s[48:49]
	s_add_u32 s48, s48, 0x80
	s_addc_u32 s49, s49, 0
	v_lshlrev_b32_e32 v98, 16, v196
	v_and_b32_e32 v99, 0xffff0000, v196
	v_lshlrev_b32_e32 v100, 16, v197
	v_and_b32_e32 v101, 0xffff0000, v197
	v_mul_f32_e32 v98, v0, v98
	v_mul_f32_e32 v99, v1, v99
	v_mul_f32_e32 v100, v2, v100
	v_mul_f32_e32 v101, v3, v101
	v_cvt_pk_bf16_f32 v64, v98, v99
	v_cvt_pk_bf16_f32 v65, v100, v101
	v_lshlrev_b32_e32 v98, 16, v198
	v_and_b32_e32 v99, 0xffff0000, v198
	v_lshlrev_b32_e32 v100, 16, v199
	v_and_b32_e32 v101, 0xffff0000, v199
	v_mul_f32_e32 v98, v4, v98
	v_mul_f32_e32 v99, v5, v99
	v_mul_f32_e32 v100, v6, v100
	v_mul_f32_e32 v101, v7, v101
	v_cvt_pk_bf16_f32 v66, v98, v99
	v_cvt_pk_bf16_f32 v67, v100, v101
	v_lshlrev_b32_e32 v98, 16, v200
	v_and_b32_e32 v99, 0xffff0000, v200
	v_lshlrev_b32_e32 v100, 16, v201
	v_and_b32_e32 v101, 0xffff0000, v201
	v_mul_f32_e32 v98, v8, v98
	v_mul_f32_e32 v99, v9, v99
	v_mul_f32_e32 v100, v10, v100
	v_mul_f32_e32 v101, v11, v101
	v_cvt_pk_bf16_f32 v68, v98, v99
	v_cvt_pk_bf16_f32 v69, v100, v101
	v_lshlrev_b32_e32 v98, 16, v202
	v_and_b32_e32 v99, 0xffff0000, v202
	v_lshlrev_b32_e32 v100, 16, v203
	v_and_b32_e32 v101, 0xffff0000, v203
	v_mul_f32_e32 v98, v12, v98
	v_mul_f32_e32 v99, v13, v99
	v_mul_f32_e32 v100, v14, v100
	v_mul_f32_e32 v101, v15, v101
	v_cvt_pk_bf16_f32 v70, v98, v99
	v_cvt_pk_bf16_f32 v71, v100, v101
	v_lshlrev_b32_e32 v98, 16, v204
	v_and_b32_e32 v99, 0xffff0000, v204
	v_lshlrev_b32_e32 v100, 16, v205
	v_and_b32_e32 v101, 0xffff0000, v205
	v_mul_f32_e32 v98, v32, v98
	v_mul_f32_e32 v99, v33, v99
	v_mul_f32_e32 v100, v34, v100
	v_mul_f32_e32 v101, v35, v101
	v_cvt_pk_bf16_f32 v72, v98, v99
	v_cvt_pk_bf16_f32 v73, v100, v101
	v_lshlrev_b32_e32 v98, 16, v206
	v_and_b32_e32 v99, 0xffff0000, v206
	v_lshlrev_b32_e32 v100, 16, v207
	v_and_b32_e32 v101, 0xffff0000, v207
	v_mul_f32_e32 v98, v36, v98
	v_mul_f32_e32 v99, v37, v99
	v_mul_f32_e32 v100, v38, v100
	v_mul_f32_e32 v101, v39, v101
	v_cvt_pk_bf16_f32 v74, v98, v99
	v_cvt_pk_bf16_f32 v75, v100, v101
	v_lshlrev_b32_e32 v98, 16, v208
	v_and_b32_e32 v99, 0xffff0000, v208
	v_lshlrev_b32_e32 v100, 16, v209
	v_and_b32_e32 v101, 0xffff0000, v209
	v_mul_f32_e32 v98, v40, v98
	v_mul_f32_e32 v99, v41, v99
	v_mul_f32_e32 v100, v42, v100
	v_mul_f32_e32 v101, v43, v101
	v_cvt_pk_bf16_f32 v76, v98, v99
	v_cvt_pk_bf16_f32 v77, v100, v101
	v_lshlrev_b32_e32 v98, 16, v210
	v_and_b32_e32 v99, 0xffff0000, v210
	v_lshlrev_b32_e32 v100, 16, v211
	v_and_b32_e32 v101, 0xffff0000, v211
	v_mul_f32_e32 v98, v44, v98
	v_mul_f32_e32 v99, v45, v99
	v_mul_f32_e32 v100, v46, v100
	v_mul_f32_e32 v101, v47, v101
	v_cvt_pk_bf16_f32 v78, v98, v99
	v_cvt_pk_bf16_f32 v79, v100, v101
	v_lshlrev_b32_e32 v98, 16, v212
	v_and_b32_e32 v99, 0xffff0000, v212
	v_lshlrev_b32_e32 v100, 16, v213
	v_and_b32_e32 v101, 0xffff0000, v213
	v_mul_f32_e32 v98, v16, v98
	v_mul_f32_e32 v99, v17, v99
	v_mul_f32_e32 v100, v18, v100
	v_mul_f32_e32 v101, v19, v101
	v_cvt_pk_bf16_f32 v80, v98, v99
	v_cvt_pk_bf16_f32 v81, v100, v101
	v_lshlrev_b32_e32 v98, 16, v214
	v_and_b32_e32 v99, 0xffff0000, v214
	v_lshlrev_b32_e32 v100, 16, v215
	v_and_b32_e32 v101, 0xffff0000, v215
	v_mul_f32_e32 v98, v20, v98
	v_mul_f32_e32 v99, v21, v99
	v_mul_f32_e32 v100, v22, v100
	v_mul_f32_e32 v101, v23, v101
	v_cvt_pk_bf16_f32 v82, v98, v99
	v_cvt_pk_bf16_f32 v83, v100, v101
	v_lshlrev_b32_e32 v98, 16, v216
; #define MFMA32(a, b, c) __builtin_amdgcn_mfma_f32_32x32x16_bf16((a), (b), (c), 0, 0, 0)
; DI float bf2f(bf16_t b) { return __uint_as_float(((unsigned)b) << 16); }
; DI void gemm_mid(const bf16_t* __restrict__ W, int ldw, const bf16_t* __restrict__ X, size_t ldx, int mclamp, int kts,
;                  int nkt, int m0, f32x16 (&acc)[2][2], bf16_t* lds) {
;     ...
;   for (int kt = 0; kt < nkt; ++kt) {
;     const bool more = kt + 1 < nkt;
;     if (more) GM_GLOAD(kt + 1)
;     __builtin_amdgcn_sched_barrier(0);
;     {
;       const bf16_t* wb = lds + (kt & 1) * MID_E + (wn * 64 + lr) * LDT + lh * 8;
;       const bf16_t* xb = lds + (kt & 1) * MID_E + 128 * LDT + (wm * 64 + lr) * LDT + lh * 8;
; #pragma unroll
;       for (int ks = 0; ks < 4; ++ks) {
;         const bf16x8 a0 = *(const bf16x8*)(wb + ks * 16), a1 = *(const bf16x8*)(wb + 32 * LDT + ks * 16);
;         const bf16x8 b0 = *(const bf16x8*)(xb + ks * 16), b1 = *(const bf16x8*)(xb + 32 * LDT + ks * 16);
;         acc[0][0] = MFMA32(a0, b0, acc[0][0]); acc[0][1] = MFMA32(a0, b1, acc[0][1]);
;         acc[1][0] = MFMA32(a1, b0, acc[1][0]); acc[1][1] = MFMA32(a1, b1, acc[1][1]);
;       }
;     }
;     __builtin_amdgcn_sched_barrier(0);
;     if (more) GM_LSTORE((kt + 1) & 1)
;     __syncthreads();
;   }
; DI void phase_merge(const P& p, int layer, bf16_t* sm, const Geo& ge) {
;     ...
;           for (int qd = 0; qd < 4; ++qd) {
;             const int n = nt_ * 128 + wn * 64 + nt * 32 + 8 * qd + 4 * lh;
;             typedef unsigned u32x2_t __attribute__((ext_vector_type(2)));
;             const u32x2_t gq_ = __builtin_nontemporal_load((const u32x2_t*)(mgs + ((size_t)((n3 * 1024 + n) >> 2) * T_ + m) * 4));
;             const uint2 gq = make_uint2(gq_[0], gq_[1]);
;             const unsigned z01 = zp[nt][mt][2 * qd], z23 = zp[nt][mt][2 * qd + 1];
;             const float v0 = bf2f((bf16_t)(z01 & 0xffff)) + bf2f((bf16_t)(gq.x & 0xffff)) * acc[nt][mt][4 * qd];
;             const float v1 = bf2f((bf16_t)(z01 >> 16)) + bf2f((bf16_t)(gq.x >> 16)) * acc[nt][mt][4 * qd + 1];
;             const float v2 = bf2f((bf16_t)(z23 & 0xffff)) + bf2f((bf16_t)(gq.y & 0xffff)) * acc[nt][mt][4 * qd + 2];
;             const float v3 = bf2f((bf16_t)(z23 >> 16)) + bf2f((bf16_t)(gq.y >> 16)) * acc[nt][mt][4 * qd + 3];
;             zp[nt][mt][2 * qd] = pack2(v0, v1);
;             zp[nt][mt][2 * qd + 1] = pack2(v2, v3);
;           }
	v_and_b32_e32 v99, 0xffff0000, v216
	v_lshlrev_b32_e32 v100, 16, v217
	v_and_b32_e32 v101, 0xffff0000, v217
	v_mul_f32_e32 v98, v24, v98
	v_mul_f32_e32 v99, v25, v99
	v_mul_f32_e32 v100, v26, v100
	v_mul_f32_e32 v101, v27, v101
	v_cvt_pk_bf16_f32 v84, v98, v99
	v_cvt_pk_bf16_f32 v85, v100, v101
	v_lshlrev_b32_e32 v98, 16, v218
	v_and_b32_e32 v99, 0xffff0000, v218
	v_lshlrev_b32_e32 v100, 16, v219
	v_and_b32_e32 v101, 0xffff0000, v219
	v_mul_f32_e32 v98, v28, v98
	v_mul_f32_e32 v99, v29, v99
	v_mul_f32_e32 v100, v30, v100
	v_mul_f32_e32 v101, v31, v101
	v_cvt_pk_bf16_f32 v86, v98, v99
	v_cvt_pk_bf16_f32 v87, v100, v101
	v_lshlrev_b32_e32 v98, 16, v236
	v_and_b32_e32 v99, 0xffff0000, v236
	v_lshlrev_b32_e32 v100, 16, v237
	v_and_b32_e32 v101, 0xffff0000, v237
	v_mul_f32_e32 v98, v48, v98
	v_mul_f32_e32 v99, v49, v99
	v_mul_f32_e32 v100, v50, v100
	v_mul_f32_e32 v101, v51, v101
	v_cvt_pk_bf16_f32 v90, v98, v99
	v_cvt_pk_bf16_f32 v91, v100, v101
	v_lshlrev_b32_e32 v98, 16, v238
	v_and_b32_e32 v99, 0xffff0000, v238
	v_lshlrev_b32_e32 v100, 16, v239
	v_and_b32_e32 v101, 0xffff0000, v239
	v_mul_f32_e32 v98, v52, v98
	v_mul_f32_e32 v99, v53, v99
	v_mul_f32_e32 v100, v54, v100
	v_mul_f32_e32 v101, v55, v101
	v_cvt_pk_bf16_f32 v92, v98, v99
	v_cvt_pk_bf16_f32 v93, v100, v101
	v_lshlrev_b32_e32 v98, 16, v240
	v_and_b32_e32 v99, 0xffff0000, v240
	v_lshlrev_b32_e32 v100, 16, v241
	v_and_b32_e32 v101, 0xffff0000, v241
	v_mul_f32_e32 v98, v56, v98
	v_mul_f32_e32 v99, v57, v99
	v_mul_f32_e32 v100, v58, v100
	v_mul_f32_e32 v101, v59, v101
	v_cvt_pk_bf16_f32 v94, v98, v99
	v_cvt_pk_bf16_f32 v95, v100, v101
	v_lshlrev_b32_e32 v98, 16, v242
	v_and_b32_e32 v99, 0xffff0000, v242
	v_lshlrev_b32_e32 v100, 16, v243
	v_and_b32_e32 v101, 0xffff0000, v243
	v_mul_f32_e32 v98, v60, v98
	v_mul_f32_e32 v99, v61, v99
	v_mul_f32_e32 v100, v62, v100
	v_mul_f32_e32 v101, v63, v101
	v_cvt_pk_bf16_f32 v96, v98, v99
	v_cvt_pk_bf16_f32 v97, v100, v101
	v_add_u32_e32 v190, 0x2000000, v186
	global_load_dwordx2 v[196:197], v190, s[28:29] nt
	global_load_dwordx2 v[212:213], v190, s[28:29] offset:256 nt
	v_add_u32_e32 v191, 0x2040000, v186
	global_load_dwordx2 v[198:199], v191, s[28:29] nt
	global_load_dwordx2 v[214:215], v191, s[28:29] offset:256 nt
	v_add_u32_e32 v190, 0x2080000, v186
	global_load_dwordx2 v[200:201], v190, s[28:29] nt
	global_load_dwordx2 v[216:217], v190, s[28:29] offset:256 nt
	v_add_u32_e32 v191, 0x20c0000, v186
	global_load_dwordx2 v[202:203], v191, s[28:29] nt
	global_load_dwordx2 v[218:219], v191, s[28:29] offset:256 nt
	v_add_u32_e32 v190, 0x2100000, v186
	global_load_dwordx2 v[204:205], v190, s[28:29] nt
	global_load_dwordx2 v[236:237], v190, s[28:29] offset:256 nt
	v_add_u32_e32 v191, 0x2140000, v186
	global_load_dwordx2 v[206:207], v191, s[28:29] nt
	global_load_dwordx2 v[238:239], v191, s[28:29] offset:256 nt
	v_add_u32_e32 v190, 0x2180000, v186
	global_load_dwordx2 v[208:209], v190, s[28:29] nt
	global_load_dwordx2 v[240:241], v190, s[28:29] offset:256 nt
	v_add_u32_e32 v191, 0x21c0000, v186
	global_load_dwordx2 v[210:211], v191, s[28:29] nt
	global_load_dwordx2 v[242:243], v191, s[28:29] offset:256 nt
	s_waitcnt vmcnt(28)
	s_barrier
	ds_read_b128 v[128:131], v172 offset:0
	ds_read_b128 v[120:123], v168 offset:0
	ds_read_b128 v[132:135], v172 offset:4096
	ds_read_b128 v[124:127], v168 offset:4096
	ds_read_b128 v[144:147], v173 offset:0
	ds_read_b128 v[136:139], v169 offset:0
	ds_read_b128 v[148:151], v173 offset:4096
	ds_read_b128 v[140:143], v169 offset:4096
	s_waitcnt lgkmcnt(6)
	v_mfma_f32_32x32x16_bf16 v[0:15], v[120:123], v[128:131], 0
	ds_read_b128 v[160:163], v174 offset:0
	s_waitcnt lgkmcnt(6)
	v_mfma_f32_32x32x16_bf16 v[16:31], v[120:123], v[132:135], 0
	ds_read_b128 v[152:155], v170 offset:0
	s_waitcnt lgkmcnt(6)
	v_mfma_f32_32x32x16_bf16 v[32:47], v[124:127], v[128:131], 0
	ds_read_b128 v[164:167], v174 offset:4096
	v_mfma_f32_32x32x16_bf16 v[48:63], v[124:127], v[132:135], 0
	ds_read_b128 v[156:159], v170 offset:4096
	ds_read_b128 v[128:131], v175 offset:0
	ds_read_b128 v[120:123], v171 offset:0
	ds_read_b128 v[132:135], v175 offset:4096
	ds_read_b128 v[124:127], v171 offset:4096
	s_waitcnt lgkmcnt(10)
	v_mfma_f32_32x32x16_bf16 v[0:15], v[136:139], v[144:147], v[0:15]
	s_waitcnt lgkmcnt(9)
	v_mfma_f32_32x32x16_bf16 v[16:31], v[136:139], v[148:151], v[16:31]
	s_waitcnt lgkmcnt(8)
	v_mfma_f32_32x32x16_bf16 v[32:47], v[140:143], v[144:147], v[32:47]
	v_mfma_f32_32x32x16_bf16 v[48:63], v[140:143], v[148:151], v[48:63]
	s_waitcnt vmcnt(22) lgkmcnt(0)
	s_barrier
; #define MFMA32(a, b, c) __builtin_amdgcn_mfma_f32_32x32x16_bf16((a), (b), (c), 0, 0, 0)
; DI void gemm_mid(const bf16_t* __restrict__ W, int ldw, const bf16_t* __restrict__ X, size_t ldx, int mclamp, int kts,
;                  int nkt, int m0, f32x16 (&acc)[2][2], bf16_t* lds) {
;     ...
;   for (int kt = 0; kt < nkt; ++kt) {
;     const bool more = kt + 1 < nkt;
;     if (more) GM_GLOAD(kt + 1)
;     __builtin_amdgcn_sched_barrier(0);
;     {
;       const bf16_t* wb = lds + (kt & 1) * MID_E + (wn * 64 + lr) * LDT + lh * 8;
;       const bf16_t* xb = lds + (kt & 1) * MID_E + 128 * LDT + (wm * 64 + lr) * LDT + lh * 8;
; #pragma unroll
;       for (int ks = 0; ks < 4; ++ks) {
;         const bf16x8 a0 = *(const bf16x8*)(wb + ks * 16), a1 = *(const bf16x8*)(wb + 32 * LDT + ks * 16);
;         const bf16x8 b0 = *(const bf16x8*)(xb + ks * 16), b1 = *(const bf16x8*)(xb + 32 * LDT + ks * 16);
;         acc[0][0] = MFMA32(a0, b0, acc[0][0]); acc[0][1] = MFMA32(a0, b1, acc[0][1]);
;         acc[1][0] = MFMA32(a1, b0, acc[1][0]); acc[1][1] = MFMA32(a1, b1, acc[1][1]);
;       }
;     }
;     __builtin_amdgcn_sched_barrier(0);
;     if (more) GM_LSTORE((kt + 1) & 1)
;     __syncthreads();
;   }
	v_mfma_f32_32x32x16_bf16 v[0:15], v[152:155], v[160:163], v[0:15]
	ds_read_b128 v[144:147], v172 offset:32768
	v_mfma_f32_32x32x16_bf16 v[16:31], v[152:155], v[164:167], v[16:31]
	ds_read_b128 v[136:139], v168 offset:16384
	s_mov_b32 m0, s50
	s_nop 0
	global_load_lds_dwordx4 v180, s[46:47]
	v_mfma_f32_32x32x16_bf16 v[32:47], v[156:159], v[160:163], v[32:47]
	ds_read_b128 v[148:151], v172 offset:36864
	v_mfma_f32_32x32x16_bf16 v[48:63], v[156:159], v[164:167], v[48:63]
	ds_read_b128 v[140:143], v168 offset:20480
	s_add_u32 m0, s50, 0x400
	s_nop 0
	global_load_lds_dwordx4 v181, s[46:47]
	s_add_u32 s46, s46, 0x80
	s_addc_u32 s47, s47, 0
	v_mfma_f32_32x32x16_bf16 v[0:15], v[120:123], v[128:131], v[0:15]
	ds_read_b128 v[160:163], v173 offset:32768
	v_mfma_f32_32x32x16_bf16 v[16:31], v[120:123], v[132:135], v[16:31]
	ds_read_b128 v[152:155], v169 offset:16384
	s_mov_b32 m0, s51
	s_nop 0
	global_load_lds_dwordx4 v182, s[48:49]
	v_mfma_f32_32x32x16_bf16 v[32:47], v[124:127], v[128:131], v[32:47]
	ds_read_b128 v[164:167], v173 offset:36864
	v_mfma_f32_32x32x16_bf16 v[48:63], v[124:127], v[132:135], v[48:63]
	ds_read_b128 v[156:159], v169 offset:20480
	s_add_u32 m0, s51, 0x400
	s_nop 0
	global_load_lds_dwordx4 v183, s[48:49]
	s_waitcnt lgkmcnt(6)
	v_mfma_f32_32x32x16_bf16 v[0:15], v[136:139], v[144:147], v[0:15]
	ds_read_b128 v[128:131], v174 offset:32768
	s_waitcnt lgkmcnt(6)
	v_mfma_f32_32x32x16_bf16 v[16:31], v[136:139], v[148:151], v[16:31]
	ds_read_b128 v[120:123], v170 offset:16384
	s_add_u32 m0, s51, 0x800
	s_nop 0
	global_load_lds_dwordx4 v184, s[48:49]
	s_waitcnt lgkmcnt(6)
	v_mfma_f32_32x32x16_bf16 v[32:47], v[140:143], v[144:147], v[32:47]
	ds_read_b128 v[132:135], v174 offset:36864
	v_mfma_f32_32x32x16_bf16 v[48:63], v[140:143], v[148:151], v[48:63]
	ds_read_b128 v[124:127], v170 offset:20480
	s_add_u32 m0, s51, 0xc00
	s_nop 0
	global_load_lds_dwordx4 v185, s[48:49]
	s_add_u32 s48, s48, 0x80
	s_addc_u32 s49, s49, 0
	ds_read_b128 v[144:147], v175 offset:32768
	ds_read_b128 v[136:139], v171 offset:16384
	ds_read_b128 v[148:151], v175 offset:36864
	ds_read_b128 v[140:143], v171 offset:20480
	s_waitcnt lgkmcnt(10)
	v_mfma_f32_32x32x16_bf16 v[0:15], v[152:155], v[160:163], v[0:15]
	s_waitcnt lgkmcnt(9)
	v_mfma_f32_32x32x16_bf16 v[16:31], v[152:155], v[164:167], v[16:31]
	s_waitcnt lgkmcnt(8)
	v_mfma_f32_32x32x16_bf16 v[32:47], v[156:159], v[160:163], v[32:47]
	v_mfma_f32_32x32x16_bf16 v[48:63], v[156:159], v[164:167], v[48:63]
	s_waitcnt vmcnt(22) lgkmcnt(0)
	s_barrier
	v_mfma_f32_32x32x16_bf16 v[0:15], v[120:123], v[128:131], v[0:15]
	ds_read_b128 v[160:163], v176 offset:0
	v_mfma_f32_32x32x16_bf16 v[16:31], v[120:123], v[132:135], v[16:31]
	ds_read_b128 v[152:155], v168 offset:32768
	s_add_u32 m0, s50, 0x4000
	s_nop 0
	global_load_lds_dwordx4 v180, s[46:47]
	v_mfma_f32_32x32x16_bf16 v[32:47], v[124:127], v[128:131], v[32:47]
	ds_read_b128 v[164:167], v176 offset:4096
	v_mfma_f32_32x32x16_bf16 v[48:63], v[124:127], v[132:135], v[48:63]
	ds_read_b128 v[156:159], v168 offset:36864
	s_add_u32 m0, s50, 0x4400
	s_nop 0
	global_load_lds_dwordx4 v181, s[46:47]
	s_add_u32 s46, s46, 0x80
	s_addc_u32 s47, s47, 0
	v_mfma_f32_32x32x16_bf16 v[0:15], v[136:139], v[144:147], v[0:15]
	ds_read_b128 v[128:131], v177 offset:0
	v_mfma_f32_32x32x16_bf16 v[16:31], v[136:139], v[148:151], v[16:31]
	ds_read_b128 v[120:123], v169 offset:32768
	s_add_u32 m0, s51, 0x8000
	s_nop 0
	global_load_lds_dwordx4 v182, s[48:49]
	v_mfma_f32_32x32x16_bf16 v[32:47], v[140:143], v[144:147], v[32:47]
	ds_read_b128 v[132:135], v177 offset:4096
	v_mfma_f32_32x32x16_bf16 v[48:63], v[140:143], v[148:151], v[48:63]
	ds_read_b128 v[124:127], v169 offset:36864
	s_add_u32 m0, s51, 0x8400
	s_nop 0
	global_load_lds_dwordx4 v183, s[48:49]
	s_waitcnt lgkmcnt(6)
	v_mfma_f32_32x32x16_bf16 v[0:15], v[152:155], v[160:163], v[0:15]
	ds_read_b128 v[144:147], v178 offset:0
	s_waitcnt lgkmcnt(6)
	v_mfma_f32_32x32x16_bf16 v[16:31], v[152:155], v[164:167], v[16:31]
	ds_read_b128 v[136:139], v170 offset:32768
	s_add_u32 m0, s51, 0x8800
	s_nop 0
	global_load_lds_dwordx4 v184, s[48:49]
	s_waitcnt lgkmcnt(6)
	v_mfma_f32_32x32x16_bf16 v[32:47], v[156:159], v[160:163], v[32:47]
	ds_read_b128 v[148:151], v178 offset:4096
	v_mfma_f32_32x32x16_bf16 v[48:63], v[156:159], v[164:167], v[48:63]
	ds_read_b128 v[140:143], v170 offset:36864
	s_add_u32 m0, s51, 0x8c00
	s_nop 0
	global_load_lds_dwordx4 v185, s[48:49]
	s_add_u32 s48, s48, 0x80
	s_addc_u32 s49, s49, 0
	ds_read_b128 v[160:163], v179 offset:0
	ds_read_b128 v[152:155], v171 offset:32768
	ds_read_b128 v[164:167], v179 offset:4096
	ds_read_b128 v[156:159], v171 offset:36864
	s_waitcnt lgkmcnt(10)
	v_mfma_f32_32x32x16_bf16 v[0:15], v[120:123], v[128:131], v[0:15]
	s_waitcnt lgkmcnt(9)
	v_mfma_f32_32x32x16_bf16 v[16:31], v[120:123], v[132:135], v[16:31]
	s_waitcnt lgkmcnt(8)
	v_mfma_f32_32x32x16_bf16 v[32:47], v[124:127], v[128:131], v[32:47]
	v_mfma_f32_32x32x16_bf16 v[48:63], v[124:127], v[132:135], v[48:63]
	s_waitcnt vmcnt(6) lgkmcnt(0)
	s_barrier
; #define MFMA32(a, b, c) __builtin_amdgcn_mfma_f32_32x32x16_bf16((a), (b), (c), 0, 0, 0)
; DI void gemm_mid(const bf16_t* __restrict__ W, int ldw, const bf16_t* __restrict__ X, size_t ldx, int mclamp, int kts,
;                  int nkt, int m0, f32x16 (&acc)[2][2], bf16_t* lds) {
;     ...
;   for (int kt = 0; kt < nkt; ++kt) {
;     const bool more = kt + 1 < nkt;
;     if (more) GM_GLOAD(kt + 1)
;     __builtin_amdgcn_sched_barrier(0);
;     {
;       const bf16_t* wb = lds + (kt & 1) * MID_E + (wn * 64 + lr) * LDT + lh * 8;
;       const bf16_t* xb = lds + (kt & 1) * MID_E + 128 * LDT + (wm * 64 + lr) * LDT + lh * 8;
; #pragma unroll
;       for (int ks = 0; ks < 4; ++ks) {
;         const bf16x8 a0 = *(const bf16x8*)(wb + ks * 16), a1 = *(const bf16x8*)(wb + 32 * LDT + ks * 16);
;         const bf16x8 b0 = *(const bf16x8*)(xb + ks * 16), b1 = *(const bf16x8*)(xb + 32 * LDT + ks * 16);
;         acc[0][0] = MFMA32(a0, b0, acc[0][0]); acc[0][1] = MFMA32(a0, b1, acc[0][1]);
;         acc[1][0] = MFMA32(a1, b0, acc[1][0]); acc[1][1] = MFMA32(a1, b1, acc[1][1]);
;       }
;     }
;     __builtin_amdgcn_sched_barrier(0);
;     if (more) GM_LSTORE((kt + 1) & 1)
;     __syncthreads();
;   }
	v_mfma_f32_32x32x16_bf16 v[0:15], v[136:139], v[144:147], v[0:15]
	ds_read_b128 v[128:131], v172 offset:0
	v_mfma_f32_32x32x16_bf16 v[16:31], v[136:139], v[148:151], v[16:31]
	ds_read_b128 v[120:123], v168 offset:0
	s_add_u32 m0, s50, 0x8000
	s_nop 0
	global_load_lds_dwordx4 v180, s[46:47]
	v_mfma_f32_32x32x16_bf16 v[32:47], v[140:143], v[144:147], v[32:47]
	ds_read_b128 v[132:135], v172 offset:4096
	v_mfma_f32_32x32x16_bf16 v[48:63], v[140:143], v[148:151], v[48:63]
	ds_read_b128 v[124:127], v168 offset:4096
	s_add_u32 m0, s50, 0x8400
	s_nop 0
	global_load_lds_dwordx4 v181, s[46:47]
	s_add_u32 s46, s46, 0x80
	s_addc_u32 s47, s47, 0
	v_mfma_f32_32x32x16_bf16 v[0:15], v[152:155], v[160:163], v[0:15]
	ds_read_b128 v[144:147], v173 offset:0
	v_mfma_f32_32x32x16_bf16 v[16:31], v[152:155], v[164:167], v[16:31]
	ds_read_b128 v[136:139], v169 offset:0
	s_add_u32 m0, s51, 0x10000
	s_nop 0
	global_load_lds_dwordx4 v182, s[48:49]
	v_mfma_f32_32x32x16_bf16 v[32:47], v[156:159], v[160:163], v[32:47]
	ds_read_b128 v[148:151], v173 offset:4096
	v_mfma_f32_32x32x16_bf16 v[48:63], v[156:159], v[164:167], v[48:63]
	ds_read_b128 v[140:143], v169 offset:4096
	s_add_u32 m0, s51, 0x10400
	s_nop 0
	global_load_lds_dwordx4 v183, s[48:49]
	s_waitcnt lgkmcnt(6)
	v_mfma_f32_32x32x16_bf16 v[0:15], v[120:123], v[128:131], v[0:15]
	ds_read_b128 v[160:163], v174 offset:0
	s_waitcnt lgkmcnt(6)
	v_mfma_f32_32x32x16_bf16 v[16:31], v[120:123], v[132:135], v[16:31]
	ds_read_b128 v[152:155], v170 offset:0
	s_add_u32 m0, s51, 0x10800
	s_nop 0
	global_load_lds_dwordx4 v184, s[48:49]
	s_waitcnt lgkmcnt(6)
	v_mfma_f32_32x32x16_bf16 v[32:47], v[124:127], v[128:131], v[32:47]
	ds_read_b128 v[164:167], v174 offset:4096
	v_mfma_f32_32x32x16_bf16 v[48:63], v[124:127], v[132:135], v[48:63]
	ds_read_b128 v[156:159], v170 offset:4096
	s_add_u32 m0, s51, 0x10c00
	s_nop 0
	global_load_lds_dwordx4 v185, s[48:49]
	s_add_u32 s48, s48, 0x80
	s_addc_u32 s49, s49, 0
	ds_read_b128 v[128:131], v175 offset:0
	ds_read_b128 v[120:123], v171 offset:0
	ds_read_b128 v[132:135], v175 offset:4096
	ds_read_b128 v[124:127], v171 offset:4096
	s_waitcnt lgkmcnt(10)
	v_mfma_f32_32x32x16_bf16 v[0:15], v[136:139], v[144:147], v[0:15]
	s_waitcnt lgkmcnt(9)
	v_mfma_f32_32x32x16_bf16 v[16:31], v[136:139], v[148:151], v[16:31]
	s_waitcnt lgkmcnt(8)
	v_mfma_f32_32x32x16_bf16 v[32:47], v[140:143], v[144:147], v[32:47]
	v_mfma_f32_32x32x16_bf16 v[48:63], v[140:143], v[148:151], v[48:63]
	s_waitcnt vmcnt(6) lgkmcnt(0)
	s_barrier
	v_mfma_f32_32x32x16_bf16 v[0:15], v[152:155], v[160:163], v[0:15]
	ds_read_b128 v[144:147], v172 offset:32768
	v_mfma_f32_32x32x16_bf16 v[16:31], v[152:155], v[164:167], v[16:31]
	ds_read_b128 v[136:139], v168 offset:16384
	s_mov_b32 m0, s50
	s_nop 0
	global_load_lds_dwordx4 v180, s[46:47]
	v_mfma_f32_32x32x16_bf16 v[32:47], v[156:159], v[160:163], v[32:47]
	ds_read_b128 v[148:151], v172 offset:36864
	v_mfma_f32_32x32x16_bf16 v[48:63], v[156:159], v[164:167], v[48:63]
	ds_read_b128 v[140:143], v168 offset:20480
	s_add_u32 m0, s50, 0x400
	s_nop 0
	global_load_lds_dwordx4 v181, s[46:47]
	s_add_u32 s46, s46, 0x80
	s_addc_u32 s47, s47, 0
	v_mfma_f32_32x32x16_bf16 v[0:15], v[120:123], v[128:131], v[0:15]
	ds_read_b128 v[160:163], v173 offset:32768
	v_mfma_f32_32x32x16_bf16 v[16:31], v[120:123], v[132:135], v[16:31]
	ds_read_b128 v[152:155], v169 offset:16384
	s_mov_b32 m0, s51
	s_nop 0
	global_load_lds_dwordx4 v182, s[48:49]
	v_mfma_f32_32x32x16_bf16 v[32:47], v[124:127], v[128:131], v[32:47]
	ds_read_b128 v[164:167], v173 offset:36864
	v_mfma_f32_32x32x16_bf16 v[48:63], v[124:127], v[132:135], v[48:63]
	ds_read_b128 v[156:159], v169 offset:20480
	s_add_u32 m0, s51, 0x400
	s_nop 0
	global_load_lds_dwordx4 v183, s[48:49]
	s_waitcnt lgkmcnt(6)
	v_mfma_f32_32x32x16_bf16 v[0:15], v[136:139], v[144:147], v[0:15]
	ds_read_b128 v[128:131], v174 offset:32768
	s_waitcnt lgkmcnt(6)
	v_mfma_f32_32x32x16_bf16 v[16:31], v[136:139], v[148:151], v[16:31]
	ds_read_b128 v[120:123], v170 offset:16384
	s_add_u32 m0, s51, 0x800
	s_nop 0
	global_load_lds_dwordx4 v184, s[48:49]
	s_waitcnt lgkmcnt(6)
	v_mfma_f32_32x32x16_bf16 v[32:47], v[140:143], v[144:147], v[32:47]
	ds_read_b128 v[132:135], v174 offset:36864
	v_mfma_f32_32x32x16_bf16 v[48:63], v[140:143], v[148:151], v[48:63]
	ds_read_b128 v[124:127], v170 offset:20480
	s_add_u32 m0, s51, 0xc00
	s_nop 0
	global_load_lds_dwordx4 v185, s[48:49]
	s_add_u32 s48, s48, 0x80
	s_addc_u32 s49, s49, 0
	ds_read_b128 v[144:147], v175 offset:32768
	ds_read_b128 v[136:139], v171 offset:16384
	ds_read_b128 v[148:151], v175 offset:36864
	ds_read_b128 v[140:143], v171 offset:20480
	s_waitcnt lgkmcnt(10)
	v_mfma_f32_32x32x16_bf16 v[0:15], v[152:155], v[160:163], v[0:15]
	s_waitcnt lgkmcnt(9)
	v_mfma_f32_32x32x16_bf16 v[16:31], v[152:155], v[164:167], v[16:31]
	s_waitcnt lgkmcnt(8)
	v_mfma_f32_32x32x16_bf16 v[32:47], v[156:159], v[160:163], v[32:47]
	v_mfma_f32_32x32x16_bf16 v[48:63], v[156:159], v[164:167], v[48:63]
	s_waitcnt vmcnt(6) lgkmcnt(0)
	s_barrier
; #define MFMA32(a, b, c) __builtin_amdgcn_mfma_f32_32x32x16_bf16((a), (b), (c), 0, 0, 0)
; DI void gemm_mid(const bf16_t* __restrict__ W, int ldw, const bf16_t* __restrict__ X, size_t ldx, int mclamp, int kts,
;                  int nkt, int m0, f32x16 (&acc)[2][2], bf16_t* lds) {
;     ...
;   for (int kt = 0; kt < nkt; ++kt) {
;     const bool more = kt + 1 < nkt;
;     if (more) GM_GLOAD(kt + 1)
;     __builtin_amdgcn_sched_barrier(0);
;     {
;       const bf16_t* wb = lds + (kt & 1) * MID_E + (wn * 64 + lr) * LDT + lh * 8;
;       const bf16_t* xb = lds + (kt & 1) * MID_E + 128 * LDT + (wm * 64 + lr) * LDT + lh * 8;
; #pragma unroll
;       for (int ks = 0; ks < 4; ++ks) {
;         const bf16x8 a0 = *(const bf16x8*)(wb + ks * 16), a1 = *(const bf16x8*)(wb + 32 * LDT + ks * 16);
;         const bf16x8 b0 = *(const bf16x8*)(xb + ks * 16), b1 = *(const bf16x8*)(xb + 32 * LDT + ks * 16);
;         acc[0][0] = MFMA32(a0, b0, acc[0][0]); acc[0][1] = MFMA32(a0, b1, acc[0][1]);
;         acc[1][0] = MFMA32(a1, b0, acc[1][0]); acc[1][1] = MFMA32(a1, b1, acc[1][1]);
;       }
;     }
;     __builtin_amdgcn_sched_barrier(0);
;     if (more) GM_LSTORE((kt + 1) & 1)
;     __syncthreads();
;   }
	v_mfma_f32_32x32x16_bf16 v[0:15], v[120:123], v[128:131], v[0:15]
	ds_read_b128 v[160:163], v176 offset:0
	v_mfma_f32_32x32x16_bf16 v[16:31], v[120:123], v[132:135], v[16:31]
	ds_read_b128 v[152:155], v168 offset:32768
	s_add_u32 m0, s50, 0x4000
	s_nop 0
	global_load_lds_dwordx4 v180, s[46:47]
	v_mfma_f32_32x32x16_bf16 v[32:47], v[124:127], v[128:131], v[32:47]
	ds_read_b128 v[164:167], v176 offset:4096
	v_mfma_f32_32x32x16_bf16 v[48:63], v[124:127], v[132:135], v[48:63]
	ds_read_b128 v[156:159], v168 offset:36864
	s_add_u32 m0, s50, 0x4400
	s_nop 0
	global_load_lds_dwordx4 v181, s[46:47]
	s_add_u32 s46, s46, 0x80
	s_addc_u32 s47, s47, 0
	v_mfma_f32_32x32x16_bf16 v[0:15], v[136:139], v[144:147], v[0:15]
	ds_read_b128 v[128:131], v177 offset:0
	v_mfma_f32_32x32x16_bf16 v[16:31], v[136:139], v[148:151], v[16:31]
	ds_read_b128 v[120:123], v169 offset:32768
	s_add_u32 m0, s51, 0x8000
	s_nop 0
	global_load_lds_dwordx4 v182, s[48:49]
	v_mfma_f32_32x32x16_bf16 v[32:47], v[140:143], v[144:147], v[32:47]
	ds_read_b128 v[132:135], v177 offset:4096
	v_mfma_f32_32x32x16_bf16 v[48:63], v[140:143], v[148:151], v[48:63]
	ds_read_b128 v[124:127], v169 offset:36864
	s_add_u32 m0, s51, 0x8400
	s_nop 0
	global_load_lds_dwordx4 v183, s[48:49]
	s_waitcnt lgkmcnt(6)
	v_mfma_f32_32x32x16_bf16 v[0:15], v[152:155], v[160:163], v[0:15]
	ds_read_b128 v[144:147], v178 offset:0
	s_waitcnt lgkmcnt(6)
	v_mfma_f32_32x32x16_bf16 v[16:31], v[152:155], v[164:167], v[16:31]
	ds_read_b128 v[136:139], v170 offset:32768
	s_add_u32 m0, s51, 0x8800
	s_nop 0
	global_load_lds_dwordx4 v184, s[48:49]
	s_waitcnt lgkmcnt(6)
	v_mfma_f32_32x32x16_bf16 v[32:47], v[156:159], v[160:163], v[32:47]
	ds_read_b128 v[148:151], v178 offset:4096
	v_mfma_f32_32x32x16_bf16 v[48:63], v[156:159], v[164:167], v[48:63]
	ds_read_b128 v[140:143], v170 offset:36864
	s_add_u32 m0, s51, 0x8c00
	s_nop 0
	global_load_lds_dwordx4 v185, s[48:49]
	s_add_u32 s48, s48, 0x80
	s_addc_u32 s49, s49, 0
	ds_read_b128 v[160:163], v179 offset:0
	ds_read_b128 v[152:155], v171 offset:32768
	ds_read_b128 v[164:167], v179 offset:4096
	ds_read_b128 v[156:159], v171 offset:36864
	s_waitcnt lgkmcnt(10)
	v_mfma_f32_32x32x16_bf16 v[0:15], v[120:123], v[128:131], v[0:15]
	s_waitcnt lgkmcnt(9)
	v_mfma_f32_32x32x16_bf16 v[16:31], v[120:123], v[132:135], v[16:31]
	s_waitcnt lgkmcnt(8)
	v_mfma_f32_32x32x16_bf16 v[32:47], v[124:127], v[128:131], v[32:47]
	v_mfma_f32_32x32x16_bf16 v[48:63], v[124:127], v[132:135], v[48:63]
	s_waitcnt vmcnt(6) lgkmcnt(0)
	s_barrier
	v_mfma_f32_32x32x16_bf16 v[0:15], v[136:139], v[144:147], v[0:15]
	ds_read_b128 v[128:131], v172 offset:0
	v_mfma_f32_32x32x16_bf16 v[16:31], v[136:139], v[148:151], v[16:31]
	ds_read_b128 v[120:123], v168 offset:0
	v_mfma_f32_32x32x16_bf16 v[32:47], v[140:143], v[144:147], v[32:47]
	ds_read_b128 v[132:135], v172 offset:4096
	v_mfma_f32_32x32x16_bf16 v[48:63], v[140:143], v[148:151], v[48:63]
	ds_read_b128 v[124:127], v168 offset:4096
	v_mfma_f32_32x32x16_bf16 v[0:15], v[152:155], v[160:163], v[0:15]
	ds_read_b128 v[144:147], v173 offset:0
	v_mfma_f32_32x32x16_bf16 v[16:31], v[152:155], v[164:167], v[16:31]
	ds_read_b128 v[136:139], v169 offset:0
	v_mfma_f32_32x32x16_bf16 v[32:47], v[156:159], v[160:163], v[32:47]
	ds_read_b128 v[148:151], v173 offset:4096
	v_mfma_f32_32x32x16_bf16 v[48:63], v[156:159], v[164:167], v[48:63]
	ds_read_b128 v[140:143], v169 offset:4096
	s_waitcnt lgkmcnt(6)
	v_mfma_f32_32x32x16_bf16 v[0:15], v[120:123], v[128:131], v[0:15]
	ds_read_b128 v[160:163], v174 offset:0
	s_waitcnt lgkmcnt(6)
	v_mfma_f32_32x32x16_bf16 v[16:31], v[120:123], v[132:135], v[16:31]
	ds_read_b128 v[152:155], v170 offset:0
	s_waitcnt lgkmcnt(6)
	v_mfma_f32_32x32x16_bf16 v[32:47], v[124:127], v[128:131], v[32:47]
	ds_read_b128 v[164:167], v174 offset:4096
	v_mfma_f32_32x32x16_bf16 v[48:63], v[124:127], v[132:135], v[48:63]
	ds_read_b128 v[156:159], v170 offset:4096
	ds_read_b128 v[128:131], v175 offset:0
	ds_read_b128 v[120:123], v171 offset:0
	ds_read_b128 v[132:135], v175 offset:4096
	ds_read_b128 v[124:127], v171 offset:4096
	s_waitcnt lgkmcnt(10)
	v_mfma_f32_32x32x16_bf16 v[0:15], v[136:139], v[144:147], v[0:15]
	s_waitcnt lgkmcnt(9)
	v_mfma_f32_32x32x16_bf16 v[16:31], v[136:139], v[148:151], v[16:31]
	s_waitcnt lgkmcnt(8)
	v_mfma_f32_32x32x16_bf16 v[32:47], v[140:143], v[144:147], v[32:47]
	v_mfma_f32_32x32x16_bf16 v[48:63], v[140:143], v[148:151], v[48:63]
	s_waitcnt vmcnt(0) lgkmcnt(0)
	s_barrier
	v_mfma_f32_32x32x16_bf16 v[0:15], v[152:155], v[160:163], v[0:15]
	ds_read_b128 v[144:147], v172 offset:32768
	v_mfma_f32_32x32x16_bf16 v[16:31], v[152:155], v[164:167], v[16:31]
	ds_read_b128 v[136:139], v168 offset:16384
	v_mfma_f32_32x32x16_bf16 v[32:47], v[156:159], v[160:163], v[32:47]
	ds_read_b128 v[148:151], v172 offset:36864
	v_mfma_f32_32x32x16_bf16 v[48:63], v[156:159], v[164:167], v[48:63]
	ds_read_b128 v[140:143], v168 offset:20480
	v_mfma_f32_32x32x16_bf16 v[0:15], v[120:123], v[128:131], v[0:15]
	ds_read_b128 v[160:163], v173 offset:32768
	v_mfma_f32_32x32x16_bf16 v[16:31], v[120:123], v[132:135], v[16:31]
	ds_read_b128 v[152:155], v169 offset:16384
	v_mfma_f32_32x32x16_bf16 v[32:47], v[124:127], v[128:131], v[32:47]
	ds_read_b128 v[164:167], v173 offset:36864
	v_mfma_f32_32x32x16_bf16 v[48:63], v[124:127], v[132:135], v[48:63]
	ds_read_b128 v[156:159], v169 offset:20480
	s_waitcnt lgkmcnt(6)
	v_mfma_f32_32x32x16_bf16 v[0:15], v[136:139], v[144:147], v[0:15]
	ds_read_b128 v[128:131], v174 offset:32768
	s_waitcnt lgkmcnt(6)
	v_mfma_f32_32x32x16_bf16 v[16:31], v[136:139], v[148:151], v[16:31]
	ds_read_b128 v[120:123], v170 offset:16384
	s_waitcnt lgkmcnt(6)
	v_mfma_f32_32x32x16_bf16 v[32:47], v[140:143], v[144:147], v[32:47]
	ds_read_b128 v[132:135], v174 offset:36864
	v_mfma_f32_32x32x16_bf16 v[48:63], v[140:143], v[148:151], v[48:63]
	ds_read_b128 v[124:127], v170 offset:20480
	ds_read_b128 v[144:147], v175 offset:32768
	ds_read_b128 v[136:139], v171 offset:16384
	ds_read_b128 v[148:151], v175 offset:36864
	ds_read_b128 v[140:143], v171 offset:20480
	s_waitcnt lgkmcnt(10)
	v_mfma_f32_32x32x16_bf16 v[0:15], v[152:155], v[160:163], v[0:15]
	s_waitcnt lgkmcnt(9)
	v_mfma_f32_32x32x16_bf16 v[16:31], v[152:155], v[164:167], v[16:31]
	s_waitcnt lgkmcnt(8)
	v_mfma_f32_32x32x16_bf16 v[32:47], v[156:159], v[160:163], v[32:47]
	v_mfma_f32_32x32x16_bf16 v[48:63], v[156:159], v[164:167], v[48:63]
	s_waitcnt lgkmcnt(0)
	s_barrier
; #define MFMA32(a, b, c) __builtin_amdgcn_mfma_f32_32x32x16_bf16((a), (b), (c), 0, 0, 0)
; DI float bf2f(bf16_t b) { return __uint_as_float(((unsigned)b) << 16); }
; DI unsigned pack2(float a, float b) { f32x2_t v = {a, b}; bf16x2_t r = __builtin_convertvector(v, bf16x2_t); return __builtin_bit_cast(unsigned, r); }
; DI void gemm_mid(const bf16_t* __restrict__ W, int ldw, const bf16_t* __restrict__ X, size_t ldx, int mclamp, int kts,
;                  int nkt, int m0, f32x16 (&acc)[2][2], bf16_t* lds) {
;     ...
;       for (int ks = 0; ks < 4; ++ks) {
;         const bf16x8 a0 = *(const bf16x8*)(wb + ks * 16), a1 = *(const bf16x8*)(wb + 32 * LDT + ks * 16);
;         const bf16x8 b0 = *(const bf16x8*)(xb + ks * 16), b1 = *(const bf16x8*)(xb + 32 * LDT + ks * 16);
;         acc[0][0] = MFMA32(a0, b0, acc[0][0]); acc[0][1] = MFMA32(a0, b1, acc[0][1]);
;         acc[1][0] = MFMA32(a1, b0, acc[1][0]); acc[1][1] = MFMA32(a1, b1, acc[1][1]);
;       }
; DI void phase_merge(const P& p, int layer, bf16_t* sm, const Geo& ge) {
;     ...
; #pragma unroll
;       for (int mt = 0; mt < 2; ++mt) {
;         const int m = mt_ * 256 + wm * 64 + mt * 32 + lr;
; #pragma unroll
;         for (int nt = 0; nt < 2; ++nt)
; #pragma unroll
;           for (int qd = 0; qd < 4; ++qd) {
;             const int n = nt_ * 128 + wn * 64 + nt * 32 + 8 * qd + 4 * lh;
;             typedef unsigned u32x2_t __attribute__((ext_vector_type(2)));
;             const u32x2_t gq_ = __builtin_nontemporal_load((const u32x2_t*)(mgs + ((size_t)((n3 * 1024 + n) >> 2) * T_ + m) * 4));
;             const uint2 gq = make_uint2(gq_[0], gq_[1]);
;             const unsigned z01 = zp[nt][mt][2 * qd], z23 = zp[nt][mt][2 * qd + 1];
;             const float v0 = bf2f((bf16_t)(z01 & 0xffff)) + bf2f((bf16_t)(gq.x & 0xffff)) * acc[nt][mt][4 * qd];
;             const float v1 = bf2f((bf16_t)(z01 >> 16)) + bf2f((bf16_t)(gq.x >> 16)) * acc[nt][mt][4 * qd + 1];
;             const float v2 = bf2f((bf16_t)(z23 & 0xffff)) + bf2f((bf16_t)(gq.y & 0xffff)) * acc[nt][mt][4 * qd + 2];
;             const float v3 = bf2f((bf16_t)(z23 >> 16)) + bf2f((bf16_t)(gq.y >> 16)) * acc[nt][mt][4 * qd + 3];
;             zp[nt][mt][2 * qd] = pack2(v0, v1);
;             zp[nt][mt][2 * qd + 1] = pack2(v2, v3);
;           }
	v_mfma_f32_32x32x16_bf16 v[0:15], v[120:123], v[128:131], v[0:15]
	v_mfma_f32_32x32x16_bf16 v[16:31], v[120:123], v[132:135], v[16:31]
	v_mfma_f32_32x32x16_bf16 v[32:47], v[124:127], v[128:131], v[32:47]
	v_mfma_f32_32x32x16_bf16 v[48:63], v[124:127], v[132:135], v[48:63]
	v_mfma_f32_32x32x16_bf16 v[0:15], v[136:139], v[144:147], v[0:15]
	v_mfma_f32_32x32x16_bf16 v[16:31], v[136:139], v[148:151], v[16:31]
	v_mfma_f32_32x32x16_bf16 v[32:47], v[140:143], v[144:147], v[32:47]
	v_mfma_f32_32x32x16_bf16 v[48:63], v[140:143], v[148:151], v[48:63]
	s_add_u32 s46, s46, 0xffc00
	s_addc_u32 s47, s47, 0
	s_add_u32 s48, s48, 0xfffc00
	s_addc_u32 s49, s49, 0
	s_mov_b32 m0, s50
	s_nop 0
	global_load_lds_dwordx4 v180, s[46:47]
	s_add_u32 m0, s50, 0x400
	s_nop 0
	global_load_lds_dwordx4 v181, s[46:47]
	s_add_u32 s46, s46, 0x80
	s_addc_u32 s47, s47, 0
	s_mov_b32 m0, s51
	s_nop 0
	global_load_lds_dwordx4 v182, s[48:49]
	s_add_u32 m0, s51, 0x400
	s_nop 0
	global_load_lds_dwordx4 v183, s[48:49]
	s_add_u32 m0, s51, 0x800
	s_nop 0
	global_load_lds_dwordx4 v184, s[48:49]
	s_add_u32 m0, s51, 0xc00
	s_nop 0
	global_load_lds_dwordx4 v185, s[48:49]
	s_add_u32 s48, s48, 0x80
	s_addc_u32 s49, s49, 0
	s_add_u32 m0, s50, 0x4000
	s_nop 0
	global_load_lds_dwordx4 v180, s[46:47]
	s_add_u32 m0, s50, 0x4400
	s_nop 0
	global_load_lds_dwordx4 v181, s[46:47]
	s_add_u32 s46, s46, 0x80
	s_addc_u32 s47, s47, 0
	s_add_u32 m0, s51, 0x8000
	s_nop 0
	global_load_lds_dwordx4 v182, s[48:49]
	s_add_u32 m0, s51, 0x8400
	s_nop 0
	global_load_lds_dwordx4 v183, s[48:49]
	s_add_u32 m0, s51, 0x8800
	s_nop 0
	global_load_lds_dwordx4 v184, s[48:49]
	s_add_u32 m0, s51, 0x8c00
	s_nop 0
	global_load_lds_dwordx4 v185, s[48:49]
	s_add_u32 s48, s48, 0x80
	s_addc_u32 s49, s49, 0
	s_add_u32 m0, s50, 0x8000
	s_nop 0
	global_load_lds_dwordx4 v180, s[46:47]
	s_add_u32 m0, s50, 0x8400
	s_nop 0
	global_load_lds_dwordx4 v181, s[46:47]
	s_add_u32 s46, s46, 0x80
	s_addc_u32 s47, s47, 0
	s_add_u32 m0, s51, 0x10000
	s_nop 0
	global_load_lds_dwordx4 v182, s[48:49]
	s_add_u32 m0, s51, 0x10400
	s_nop 0
	global_load_lds_dwordx4 v183, s[48:49]
	s_add_u32 m0, s51, 0x10800
	s_nop 0
	global_load_lds_dwordx4 v184, s[48:49]
	s_add_u32 m0, s51, 0x10c00
	s_nop 0
	global_load_lds_dwordx4 v185, s[48:49]
	s_add_u32 s48, s48, 0x80
	s_addc_u32 s49, s49, 0
	v_lshlrev_b32_e32 v98, 16, v196
	v_and_b32_e32 v99, 0xffff0000, v196
	v_lshlrev_b32_e32 v100, 16, v197
	v_and_b32_e32 v101, 0xffff0000, v197
	v_lshlrev_b32_e32 v102, 16, v64
	v_and_b32_e32 v103, 0xffff0000, v64
	v_lshlrev_b32_e32 v104, 16, v65
	v_and_b32_e32 v105, 0xffff0000, v65
	v_fma_f32 v98, v0, v98, v102
	v_fma_f32 v99, v1, v99, v103
	v_fma_f32 v100, v2, v100, v104
	v_fma_f32 v101, v3, v101, v105
	v_cvt_pk_bf16_f32 v64, v98, v99
	v_cvt_pk_bf16_f32 v65, v100, v101
	v_lshlrev_b32_e32 v98, 16, v198
	v_and_b32_e32 v99, 0xffff0000, v198
	v_lshlrev_b32_e32 v100, 16, v199
	v_and_b32_e32 v101, 0xffff0000, v199
	v_lshlrev_b32_e32 v102, 16, v66
	v_and_b32_e32 v103, 0xffff0000, v66
	v_lshlrev_b32_e32 v104, 16, v67
	v_and_b32_e32 v105, 0xffff0000, v67
	v_fma_f32 v98, v4, v98, v102
	v_fma_f32 v99, v5, v99, v103
	v_fma_f32 v100, v6, v100, v104
	v_fma_f32 v101, v7, v101, v105
	v_cvt_pk_bf16_f32 v66, v98, v99
	v_cvt_pk_bf16_f32 v67, v100, v101
	v_lshlrev_b32_e32 v98, 16, v200
	v_and_b32_e32 v99, 0xffff0000, v200
	v_lshlrev_b32_e32 v100, 16, v201
	v_and_b32_e32 v101, 0xffff0000, v201
	v_lshlrev_b32_e32 v102, 16, v68
	v_and_b32_e32 v103, 0xffff0000, v68
	v_lshlrev_b32_e32 v104, 16, v69
	v_and_b32_e32 v105, 0xffff0000, v69
	v_fma_f32 v98, v8, v98, v102
	v_fma_f32 v99, v9, v99, v103
	v_fma_f32 v100, v10, v100, v104
	v_fma_f32 v101, v11, v101, v105
	v_cvt_pk_bf16_f32 v68, v98, v99
	v_cvt_pk_bf16_f32 v69, v100, v101
	v_lshlrev_b32_e32 v98, 16, v202
	v_and_b32_e32 v99, 0xffff0000, v202
	v_lshlrev_b32_e32 v100, 16, v203
	v_and_b32_e32 v101, 0xffff0000, v203
	v_lshlrev_b32_e32 v102, 16, v70
	v_and_b32_e32 v103, 0xffff0000, v70
	v_lshlrev_b32_e32 v104, 16, v71
	v_and_b32_e32 v105, 0xffff0000, v71
	v_fma_f32 v98, v12, v98, v102
	v_fma_f32 v99, v13, v99, v103
	v_fma_f32 v100, v14, v100, v104
	v_fma_f32 v101, v15, v101, v105
	v_cvt_pk_bf16_f32 v70, v98, v99
	v_cvt_pk_bf16_f32 v71, v100, v101
	v_lshlrev_b32_e32 v98, 16, v204
	v_and_b32_e32 v99, 0xffff0000, v204
	v_lshlrev_b32_e32 v100, 16, v205
	v_and_b32_e32 v101, 0xffff0000, v205
	v_lshlrev_b32_e32 v102, 16, v72
	v_and_b32_e32 v103, 0xffff0000, v72
	v_lshlrev_b32_e32 v104, 16, v73
	v_and_b32_e32 v105, 0xffff0000, v73
	v_fma_f32 v98, v32, v98, v102
	v_fma_f32 v99, v33, v99, v103
	v_fma_f32 v100, v34, v100, v104
	v_fma_f32 v101, v35, v101, v105
	v_cvt_pk_bf16_f32 v72, v98, v99
	v_cvt_pk_bf16_f32 v73, v100, v101
	v_lshlrev_b32_e32 v98, 16, v206
	v_and_b32_e32 v99, 0xffff0000, v206
	v_lshlrev_b32_e32 v100, 16, v207
	v_and_b32_e32 v101, 0xffff0000, v207
	v_lshlrev_b32_e32 v102, 16, v74
	v_and_b32_e32 v103, 0xffff0000, v74
	v_lshlrev_b32_e32 v104, 16, v75
	v_and_b32_e32 v105, 0xffff0000, v75
	v_fma_f32 v98, v36, v98, v102
	v_fma_f32 v99, v37, v99, v103
	v_fma_f32 v100, v38, v100, v104
	v_fma_f32 v101, v39, v101, v105
	v_cvt_pk_bf16_f32 v74, v98, v99
	v_cvt_pk_bf16_f32 v75, v100, v101
	v_lshlrev_b32_e32 v98, 16, v208
	v_and_b32_e32 v99, 0xffff0000, v208
	v_lshlrev_b32_e32 v100, 16, v209
	v_and_b32_e32 v101, 0xffff0000, v209
	v_lshlrev_b32_e32 v102, 16, v76
	v_and_b32_e32 v103, 0xffff0000, v76
	v_lshlrev_b32_e32 v104, 16, v77
	v_and_b32_e32 v105, 0xffff0000, v77
	v_fma_f32 v98, v40, v98, v102
	v_fma_f32 v99, v41, v99, v103
	v_fma_f32 v100, v42, v100, v104
	v_fma_f32 v101, v43, v101, v105
	v_cvt_pk_bf16_f32 v76, v98, v99
	v_cvt_pk_bf16_f32 v77, v100, v101
; #define MFMA32(a, b, c) __builtin_amdgcn_mfma_f32_32x32x16_bf16((a), (b), (c), 0, 0, 0)
; DI float bf2f(bf16_t b) { return __uint_as_float(((unsigned)b) << 16); }
; DI void gemm_mid(const bf16_t* __restrict__ W, int ldw, const bf16_t* __restrict__ X, size_t ldx, int mclamp, int kts,
;                  int nkt, int m0, f32x16 (&acc)[2][2], bf16_t* lds) {
;     ...
;   for (int kt = 0; kt < nkt; ++kt) {
;     const bool more = kt + 1 < nkt;
;     if (more) GM_GLOAD(kt + 1)
;     __builtin_amdgcn_sched_barrier(0);
;     {
;       const bf16_t* wb = lds + (kt & 1) * MID_E + (wn * 64 + lr) * LDT + lh * 8;
;       const bf16_t* xb = lds + (kt & 1) * MID_E + 128 * LDT + (wm * 64 + lr) * LDT + lh * 8;
; #pragma unroll
;       for (int ks = 0; ks < 4; ++ks) {
;         const bf16x8 a0 = *(const bf16x8*)(wb + ks * 16), a1 = *(const bf16x8*)(wb + 32 * LDT + ks * 16);
;         const bf16x8 b0 = *(const bf16x8*)(xb + ks * 16), b1 = *(const bf16x8*)(xb + 32 * LDT + ks * 16);
;         acc[0][0] = MFMA32(a0, b0, acc[0][0]); acc[0][1] = MFMA32(a0, b1, acc[0][1]);
;         acc[1][0] = MFMA32(a1, b0, acc[1][0]); acc[1][1] = MFMA32(a1, b1, acc[1][1]);
;       }
;     }
;     __builtin_amdgcn_sched_barrier(0);
;     if (more) GM_LSTORE((kt + 1) & 1)
;     __syncthreads();
;   }
; DI void phase_merge(const P& p, int layer, bf16_t* sm, const Geo& ge) {
;     ...
;           for (int qd = 0; qd < 4; ++qd) {
;             const int n = nt_ * 128 + wn * 64 + nt * 32 + 8 * qd + 4 * lh;
;             typedef unsigned u32x2_t __attribute__((ext_vector_type(2)));
;             const u32x2_t gq_ = __builtin_nontemporal_load((const u32x2_t*)(mgs + ((size_t)((n3 * 1024 + n) >> 2) * T_ + m) * 4));
;             const uint2 gq = make_uint2(gq_[0], gq_[1]);
;             const unsigned z01 = zp[nt][mt][2 * qd], z23 = zp[nt][mt][2 * qd + 1];
;             const float v0 = bf2f((bf16_t)(z01 & 0xffff)) + bf2f((bf16_t)(gq.x & 0xffff)) * acc[nt][mt][4 * qd];
;             const float v1 = bf2f((bf16_t)(z01 >> 16)) + bf2f((bf16_t)(gq.x >> 16)) * acc[nt][mt][4 * qd + 1];
;             const float v2 = bf2f((bf16_t)(z23 & 0xffff)) + bf2f((bf16_t)(gq.y & 0xffff)) * acc[nt][mt][4 * qd + 2];
;             const float v3 = bf2f((bf16_t)(z23 >> 16)) + bf2f((bf16_t)(gq.y >> 16)) * acc[nt][mt][4 * qd + 3];
;             zp[nt][mt][2 * qd] = pack2(v0, v1);
;             zp[nt][mt][2 * qd + 1] = pack2(v2, v3);
;           }
	v_lshlrev_b32_e32 v98, 16, v210
	v_and_b32_e32 v99, 0xffff0000, v210
	v_lshlrev_b32_e32 v100, 16, v211
	v_and_b32_e32 v101, 0xffff0000, v211
	v_lshlrev_b32_e32 v102, 16, v78
	v_and_b32_e32 v103, 0xffff0000, v78
	v_lshlrev_b32_e32 v104, 16, v79
	v_and_b32_e32 v105, 0xffff0000, v79
	v_fma_f32 v98, v44, v98, v102
	v_fma_f32 v99, v45, v99, v103
	v_fma_f32 v100, v46, v100, v104
	v_fma_f32 v101, v47, v101, v105
	v_cvt_pk_bf16_f32 v78, v98, v99
	v_cvt_pk_bf16_f32 v79, v100, v101
	v_lshlrev_b32_e32 v98, 16, v212
	v_and_b32_e32 v99, 0xffff0000, v212
	v_lshlrev_b32_e32 v100, 16, v213
	v_and_b32_e32 v101, 0xffff0000, v213
	v_lshlrev_b32_e32 v102, 16, v80
	v_and_b32_e32 v103, 0xffff0000, v80
	v_lshlrev_b32_e32 v104, 16, v81
	v_and_b32_e32 v105, 0xffff0000, v81
	v_fma_f32 v98, v16, v98, v102
	v_fma_f32 v99, v17, v99, v103
	v_fma_f32 v100, v18, v100, v104
	v_fma_f32 v101, v19, v101, v105
	v_cvt_pk_bf16_f32 v80, v98, v99
	v_cvt_pk_bf16_f32 v81, v100, v101
	v_lshlrev_b32_e32 v98, 16, v214
	v_and_b32_e32 v99, 0xffff0000, v214
	v_lshlrev_b32_e32 v100, 16, v215
	v_and_b32_e32 v101, 0xffff0000, v215
	v_lshlrev_b32_e32 v102, 16, v82
	v_and_b32_e32 v103, 0xffff0000, v82
	v_lshlrev_b32_e32 v104, 16, v83
	v_and_b32_e32 v105, 0xffff0000, v83
	v_fma_f32 v98, v20, v98, v102
	v_fma_f32 v99, v21, v99, v103
	v_fma_f32 v100, v22, v100, v104
	v_fma_f32 v101, v23, v101, v105
	v_cvt_pk_bf16_f32 v82, v98, v99
	v_cvt_pk_bf16_f32 v83, v100, v101
	v_lshlrev_b32_e32 v98, 16, v216
	v_and_b32_e32 v99, 0xffff0000, v216
	v_lshlrev_b32_e32 v100, 16, v217
	v_and_b32_e32 v101, 0xffff0000, v217
	v_lshlrev_b32_e32 v102, 16, v84
	v_and_b32_e32 v103, 0xffff0000, v84
	v_lshlrev_b32_e32 v104, 16, v85
	v_and_b32_e32 v105, 0xffff0000, v85
	v_fma_f32 v98, v24, v98, v102
	v_fma_f32 v99, v25, v99, v103
	v_fma_f32 v100, v26, v100, v104
	v_fma_f32 v101, v27, v101, v105
	v_cvt_pk_bf16_f32 v84, v98, v99
	v_cvt_pk_bf16_f32 v85, v100, v101
	v_lshlrev_b32_e32 v98, 16, v218
	v_and_b32_e32 v99, 0xffff0000, v218
	v_lshlrev_b32_e32 v100, 16, v219
	v_and_b32_e32 v101, 0xffff0000, v219
	v_lshlrev_b32_e32 v102, 16, v86
	v_and_b32_e32 v103, 0xffff0000, v86
	v_lshlrev_b32_e32 v104, 16, v87
	v_and_b32_e32 v105, 0xffff0000, v87
	v_fma_f32 v98, v28, v98, v102
	v_fma_f32 v99, v29, v99, v103
	v_fma_f32 v100, v30, v100, v104
	v_fma_f32 v101, v31, v101, v105
	v_cvt_pk_bf16_f32 v86, v98, v99
	v_cvt_pk_bf16_f32 v87, v100, v101
	v_lshlrev_b32_e32 v98, 16, v236
	v_and_b32_e32 v99, 0xffff0000, v236
	v_lshlrev_b32_e32 v100, 16, v237
	v_and_b32_e32 v101, 0xffff0000, v237
	v_lshlrev_b32_e32 v102, 16, v90
	v_and_b32_e32 v103, 0xffff0000, v90
	v_lshlrev_b32_e32 v104, 16, v91
	v_and_b32_e32 v105, 0xffff0000, v91
	v_fma_f32 v98, v48, v98, v102
	v_fma_f32 v99, v49, v99, v103
	v_fma_f32 v100, v50, v100, v104
	v_fma_f32 v101, v51, v101, v105
	v_cvt_pk_bf16_f32 v90, v98, v99
	v_cvt_pk_bf16_f32 v91, v100, v101
	v_lshlrev_b32_e32 v98, 16, v238
	v_and_b32_e32 v99, 0xffff0000, v238
	v_lshlrev_b32_e32 v100, 16, v239
	v_and_b32_e32 v101, 0xffff0000, v239
	v_lshlrev_b32_e32 v102, 16, v92
	v_and_b32_e32 v103, 0xffff0000, v92
	v_lshlrev_b32_e32 v104, 16, v93
	v_and_b32_e32 v105, 0xffff0000, v93
	v_fma_f32 v98, v52, v98, v102
	v_fma_f32 v99, v53, v99, v103
	v_fma_f32 v100, v54, v100, v104
	v_fma_f32 v101, v55, v101, v105
	v_cvt_pk_bf16_f32 v92, v98, v99
	v_cvt_pk_bf16_f32 v93, v100, v101
	v_lshlrev_b32_e32 v98, 16, v240
	v_and_b32_e32 v99, 0xffff0000, v240
	v_lshlrev_b32_e32 v100, 16, v241
	v_and_b32_e32 v101, 0xffff0000, v241
	v_lshlrev_b32_e32 v102, 16, v94
	v_and_b32_e32 v103, 0xffff0000, v94
	v_lshlrev_b32_e32 v104, 16, v95
	v_and_b32_e32 v105, 0xffff0000, v95
	v_fma_f32 v98, v56, v98, v102
	v_fma_f32 v99, v57, v99, v103
	v_fma_f32 v100, v58, v100, v104
	v_fma_f32 v101, v59, v101, v105
	v_cvt_pk_bf16_f32 v94, v98, v99
	v_cvt_pk_bf16_f32 v95, v100, v101
	v_lshlrev_b32_e32 v98, 16, v242
	v_and_b32_e32 v99, 0xffff0000, v242
	v_lshlrev_b32_e32 v100, 16, v243
	v_and_b32_e32 v101, 0xffff0000, v243
	v_lshlrev_b32_e32 v102, 16, v96
	v_and_b32_e32 v103, 0xffff0000, v96
	v_lshlrev_b32_e32 v104, 16, v97
	v_and_b32_e32 v105, 0xffff0000, v97
	v_fma_f32 v98, v60, v98, v102
	v_fma_f32 v99, v61, v99, v103
	v_fma_f32 v100, v62, v100, v104
	v_fma_f32 v101, v63, v101, v105
	v_cvt_pk_bf16_f32 v96, v98, v99
	v_cvt_pk_bf16_f32 v97, v100, v101
	v_add_u32_e32 v190, 0x4000000, v186
	global_load_dwordx2 v[196:197], v190, s[28:29] nt
	global_load_dwordx2 v[212:213], v190, s[28:29] offset:256 nt
	v_add_u32_e32 v191, 0x4040000, v186
	global_load_dwordx2 v[198:199], v191, s[28:29] nt
	global_load_dwordx2 v[214:215], v191, s[28:29] offset:256 nt
	v_add_u32_e32 v190, 0x4080000, v186
	global_load_dwordx2 v[200:201], v190, s[28:29] nt
	global_load_dwordx2 v[216:217], v190, s[28:29] offset:256 nt
	v_add_u32_e32 v191, 0x40c0000, v186
	global_load_dwordx2 v[202:203], v191, s[28:29] nt
	global_load_dwordx2 v[218:219], v191, s[28:29] offset:256 nt
	v_add_u32_e32 v190, 0x4100000, v186
	global_load_dwordx2 v[204:205], v190, s[28:29] nt
	global_load_dwordx2 v[236:237], v190, s[28:29] offset:256 nt
	v_add_u32_e32 v191, 0x4140000, v186
	global_load_dwordx2 v[206:207], v191, s[28:29] nt
	global_load_dwordx2 v[238:239], v191, s[28:29] offset:256 nt
	v_add_u32_e32 v190, 0x4180000, v186
	global_load_dwordx2 v[208:209], v190, s[28:29] nt
	global_load_dwordx2 v[240:241], v190, s[28:29] offset:256 nt
	v_add_u32_e32 v191, 0x41c0000, v186
	global_load_dwordx2 v[210:211], v191, s[28:29] nt
	global_load_dwordx2 v[242:243], v191, s[28:29] offset:256 nt
	s_waitcnt vmcnt(28)
	s_barrier
; #define MFMA32(a, b, c) __builtin_amdgcn_mfma_f32_32x32x16_bf16((a), (b), (c), 0, 0, 0)
; DI void gemm_mid(const bf16_t* __restrict__ W, int ldw, const bf16_t* __restrict__ X, size_t ldx, int mclamp, int kts,
;                  int nkt, int m0, f32x16 (&acc)[2][2], bf16_t* lds) {
;     ...
;   for (int kt = 0; kt < nkt; ++kt) {
;     const bool more = kt + 1 < nkt;
;     if (more) GM_GLOAD(kt + 1)
;     __builtin_amdgcn_sched_barrier(0);
;     {
;       const bf16_t* wb = lds + (kt & 1) * MID_E + (wn * 64 + lr) * LDT + lh * 8;
;       const bf16_t* xb = lds + (kt & 1) * MID_E + 128 * LDT + (wm * 64 + lr) * LDT + lh * 8;
; #pragma unroll
;       for (int ks = 0; ks < 4; ++ks) {
;         const bf16x8 a0 = *(const bf16x8*)(wb + ks * 16), a1 = *(const bf16x8*)(wb + 32 * LDT + ks * 16);
;         const bf16x8 b0 = *(const bf16x8*)(xb + ks * 16), b1 = *(const bf16x8*)(xb + 32 * LDT + ks * 16);
;         acc[0][0] = MFMA32(a0, b0, acc[0][0]); acc[0][1] = MFMA32(a0, b1, acc[0][1]);
;         acc[1][0] = MFMA32(a1, b0, acc[1][0]); acc[1][1] = MFMA32(a1, b1, acc[1][1]);
;       }
;     }
;     __builtin_amdgcn_sched_barrier(0);
;     if (more) GM_LSTORE((kt + 1) & 1)
;     __syncthreads();
;   }
	ds_read_b128 v[128:131], v172 offset:0
	ds_read_b128 v[120:123], v168 offset:0
	ds_read_b128 v[132:135], v172 offset:4096
	ds_read_b128 v[124:127], v168 offset:4096
	ds_read_b128 v[144:147], v173 offset:0
	ds_read_b128 v[136:139], v169 offset:0
	ds_read_b128 v[148:151], v173 offset:4096
	ds_read_b128 v[140:143], v169 offset:4096
	s_waitcnt lgkmcnt(6)
	v_mfma_f32_32x32x16_bf16 v[0:15], v[120:123], v[128:131], 0
	ds_read_b128 v[160:163], v174 offset:0
	s_waitcnt lgkmcnt(6)
	v_mfma_f32_32x32x16_bf16 v[16:31], v[120:123], v[132:135], 0
	ds_read_b128 v[152:155], v170 offset:0
	s_waitcnt lgkmcnt(6)
	v_mfma_f32_32x32x16_bf16 v[32:47], v[124:127], v[128:131], 0
	ds_read_b128 v[164:167], v174 offset:4096
	v_mfma_f32_32x32x16_bf16 v[48:63], v[124:127], v[132:135], 0
	ds_read_b128 v[156:159], v170 offset:4096
	ds_read_b128 v[128:131], v175 offset:0
	ds_read_b128 v[120:123], v171 offset:0
	ds_read_b128 v[132:135], v175 offset:4096
	ds_read_b128 v[124:127], v171 offset:4096
	s_waitcnt lgkmcnt(10)
	v_mfma_f32_32x32x16_bf16 v[0:15], v[136:139], v[144:147], v[0:15]
	s_waitcnt lgkmcnt(9)
	v_mfma_f32_32x32x16_bf16 v[16:31], v[136:139], v[148:151], v[16:31]
	s_waitcnt lgkmcnt(8)
	v_mfma_f32_32x32x16_bf16 v[32:47], v[140:143], v[144:147], v[32:47]
	v_mfma_f32_32x32x16_bf16 v[48:63], v[140:143], v[148:151], v[48:63]
	s_waitcnt vmcnt(22) lgkmcnt(0)
	s_barrier
	v_mfma_f32_32x32x16_bf16 v[0:15], v[152:155], v[160:163], v[0:15]
	ds_read_b128 v[144:147], v172 offset:32768
	v_mfma_f32_32x32x16_bf16 v[16:31], v[152:155], v[164:167], v[16:31]
	ds_read_b128 v[136:139], v168 offset:16384
	s_mov_b32 m0, s50
	s_nop 0
	global_load_lds_dwordx4 v180, s[46:47]
	v_mfma_f32_32x32x16_bf16 v[32:47], v[156:159], v[160:163], v[32:47]
	ds_read_b128 v[148:151], v172 offset:36864
	v_mfma_f32_32x32x16_bf16 v[48:63], v[156:159], v[164:167], v[48:63]
	ds_read_b128 v[140:143], v168 offset:20480
	s_add_u32 m0, s50, 0x400
	s_nop 0
	global_load_lds_dwordx4 v181, s[46:47]
	s_add_u32 s46, s46, 0x80
	s_addc_u32 s47, s47, 0
	v_mfma_f32_32x32x16_bf16 v[0:15], v[120:123], v[128:131], v[0:15]
	ds_read_b128 v[160:163], v173 offset:32768
	v_mfma_f32_32x32x16_bf16 v[16:31], v[120:123], v[132:135], v[16:31]
	ds_read_b128 v[152:155], v169 offset:16384
	s_mov_b32 m0, s51
	s_nop 0
	global_load_lds_dwordx4 v182, s[48:49]
	v_mfma_f32_32x32x16_bf16 v[32:47], v[124:127], v[128:131], v[32:47]
	ds_read_b128 v[164:167], v173 offset:36864
	v_mfma_f32_32x32x16_bf16 v[48:63], v[124:127], v[132:135], v[48:63]
	ds_read_b128 v[156:159], v169 offset:20480
	s_add_u32 m0, s51, 0x400
	s_nop 0
	global_load_lds_dwordx4 v183, s[48:49]
	s_waitcnt lgkmcnt(6)
	v_mfma_f32_32x32x16_bf16 v[0:15], v[136:139], v[144:147], v[0:15]
	ds_read_b128 v[128:131], v174 offset:32768
	s_waitcnt lgkmcnt(6)
	v_mfma_f32_32x32x16_bf16 v[16:31], v[136:139], v[148:151], v[16:31]
	ds_read_b128 v[120:123], v170 offset:16384
	s_add_u32 m0, s51, 0x800
	s_nop 0
	global_load_lds_dwordx4 v184, s[48:49]
	s_waitcnt lgkmcnt(6)
	v_mfma_f32_32x32x16_bf16 v[32:47], v[140:143], v[144:147], v[32:47]
	ds_read_b128 v[132:135], v174 offset:36864
	v_mfma_f32_32x32x16_bf16 v[48:63], v[140:143], v[148:151], v[48:63]
	ds_read_b128 v[124:127], v170 offset:20480
	s_add_u32 m0, s51, 0xc00
	s_nop 0
	global_load_lds_dwordx4 v185, s[48:49]
	s_add_u32 s48, s48, 0x80
	s_addc_u32 s49, s49, 0
	ds_read_b128 v[144:147], v175 offset:32768
	ds_read_b128 v[136:139], v171 offset:16384
	ds_read_b128 v[148:151], v175 offset:36864
	ds_read_b128 v[140:143], v171 offset:20480
	s_waitcnt lgkmcnt(10)
	v_mfma_f32_32x32x16_bf16 v[0:15], v[152:155], v[160:163], v[0:15]
	s_waitcnt lgkmcnt(9)
	v_mfma_f32_32x32x16_bf16 v[16:31], v[152:155], v[164:167], v[16:31]
	s_waitcnt lgkmcnt(8)
	v_mfma_f32_32x32x16_bf16 v[32:47], v[156:159], v[160:163], v[32:47]
	v_mfma_f32_32x32x16_bf16 v[48:63], v[156:159], v[164:167], v[48:63]
	s_waitcnt vmcnt(22) lgkmcnt(0)
	s_barrier
	v_mfma_f32_32x32x16_bf16 v[0:15], v[120:123], v[128:131], v[0:15]
	ds_read_b128 v[160:163], v176 offset:0
	v_mfma_f32_32x32x16_bf16 v[16:31], v[120:123], v[132:135], v[16:31]
	ds_read_b128 v[152:155], v168 offset:32768
	s_add_u32 m0, s50, 0x4000
	s_nop 0
	global_load_lds_dwordx4 v180, s[46:47]
	v_mfma_f32_32x32x16_bf16 v[32:47], v[124:127], v[128:131], v[32:47]
	ds_read_b128 v[164:167], v176 offset:4096
	v_mfma_f32_32x32x16_bf16 v[48:63], v[124:127], v[132:135], v[48:63]
	ds_read_b128 v[156:159], v168 offset:36864
	s_add_u32 m0, s50, 0x4400
	s_nop 0
	global_load_lds_dwordx4 v181, s[46:47]
	s_add_u32 s46, s46, 0x80
	s_addc_u32 s47, s47, 0
	v_mfma_f32_32x32x16_bf16 v[0:15], v[136:139], v[144:147], v[0:15]
	ds_read_b128 v[128:131], v177 offset:0
	v_mfma_f32_32x32x16_bf16 v[16:31], v[136:139], v[148:151], v[16:31]
	ds_read_b128 v[120:123], v169 offset:32768
	s_add_u32 m0, s51, 0x8000
	s_nop 0
	global_load_lds_dwordx4 v182, s[48:49]
	v_mfma_f32_32x32x16_bf16 v[32:47], v[140:143], v[144:147], v[32:47]
	ds_read_b128 v[132:135], v177 offset:4096
	v_mfma_f32_32x32x16_bf16 v[48:63], v[140:143], v[148:151], v[48:63]
	ds_read_b128 v[124:127], v169 offset:36864
	s_add_u32 m0, s51, 0x8400
	s_nop 0
	global_load_lds_dwordx4 v183, s[48:49]
	s_waitcnt lgkmcnt(6)
	v_mfma_f32_32x32x16_bf16 v[0:15], v[152:155], v[160:163], v[0:15]
	ds_read_b128 v[144:147], v178 offset:0
	s_waitcnt lgkmcnt(6)
	v_mfma_f32_32x32x16_bf16 v[16:31], v[152:155], v[164:167], v[16:31]
	ds_read_b128 v[136:139], v170 offset:32768
	s_add_u32 m0, s51, 0x8800
	s_nop 0
	global_load_lds_dwordx4 v184, s[48:49]
	s_waitcnt lgkmcnt(6)
	v_mfma_f32_32x32x16_bf16 v[32:47], v[156:159], v[160:163], v[32:47]
	ds_read_b128 v[148:151], v178 offset:4096
	v_mfma_f32_32x32x16_bf16 v[48:63], v[156:159], v[164:167], v[48:63]
	ds_read_b128 v[140:143], v170 offset:36864
	s_add_u32 m0, s51, 0x8c00
	s_nop 0
	global_load_lds_dwordx4 v185, s[48:49]
	s_add_u32 s48, s48, 0x80
	s_addc_u32 s49, s49, 0
	ds_read_b128 v[160:163], v179 offset:0
	ds_read_b128 v[152:155], v171 offset:32768
	ds_read_b128 v[164:167], v179 offset:4096
	ds_read_b128 v[156:159], v171 offset:36864
	s_waitcnt lgkmcnt(10)
	v_mfma_f32_32x32x16_bf16 v[0:15], v[120:123], v[128:131], v[0:15]
	s_waitcnt lgkmcnt(9)
	v_mfma_f32_32x32x16_bf16 v[16:31], v[120:123], v[132:135], v[16:31]
	s_waitcnt lgkmcnt(8)
	v_mfma_f32_32x32x16_bf16 v[32:47], v[124:127], v[128:131], v[32:47]
	v_mfma_f32_32x32x16_bf16 v[48:63], v[124:127], v[132:135], v[48:63]
	s_waitcnt vmcnt(6) lgkmcnt(0)
	s_barrier
; #define MFMA32(a, b, c) __builtin_amdgcn_mfma_f32_32x32x16_bf16((a), (b), (c), 0, 0, 0)
; DI void gemm_mid(const bf16_t* __restrict__ W, int ldw, const bf16_t* __restrict__ X, size_t ldx, int mclamp, int kts,
;                  int nkt, int m0, f32x16 (&acc)[2][2], bf16_t* lds) {
;     ...
;   for (int kt = 0; kt < nkt; ++kt) {
;     const bool more = kt + 1 < nkt;
;     if (more) GM_GLOAD(kt + 1)
;     __builtin_amdgcn_sched_barrier(0);
;     {
;       const bf16_t* wb = lds + (kt & 1) * MID_E + (wn * 64 + lr) * LDT + lh * 8;
;       const bf16_t* xb = lds + (kt & 1) * MID_E + 128 * LDT + (wm * 64 + lr) * LDT + lh * 8;
; #pragma unroll
;       for (int ks = 0; ks < 4; ++ks) {
;         const bf16x8 a0 = *(const bf16x8*)(wb + ks * 16), a1 = *(const bf16x8*)(wb + 32 * LDT + ks * 16);
;         const bf16x8 b0 = *(const bf16x8*)(xb + ks * 16), b1 = *(const bf16x8*)(xb + 32 * LDT + ks * 16);
;         acc[0][0] = MFMA32(a0, b0, acc[0][0]); acc[0][1] = MFMA32(a0, b1, acc[0][1]);
;         acc[1][0] = MFMA32(a1, b0, acc[1][0]); acc[1][1] = MFMA32(a1, b1, acc[1][1]);
;       }
;     }
;     __builtin_amdgcn_sched_barrier(0);
;     if (more) GM_LSTORE((kt + 1) & 1)
;     __syncthreads();
;   }
	v_mfma_f32_32x32x16_bf16 v[0:15], v[136:139], v[144:147], v[0:15]
	ds_read_b128 v[128:131], v172 offset:0
	v_mfma_f32_32x32x16_bf16 v[16:31], v[136:139], v[148:151], v[16:31]
	ds_read_b128 v[120:123], v168 offset:0
	s_add_u32 m0, s50, 0x8000
	s_nop 0
	global_load_lds_dwordx4 v180, s[46:47]
	v_mfma_f32_32x32x16_bf16 v[32:47], v[140:143], v[144:147], v[32:47]
	ds_read_b128 v[132:135], v172 offset:4096
	v_mfma_f32_32x32x16_bf16 v[48:63], v[140:143], v[148:151], v[48:63]
	ds_read_b128 v[124:127], v168 offset:4096
	s_add_u32 m0, s50, 0x8400
	s_nop 0
	global_load_lds_dwordx4 v181, s[46:47]
	s_add_u32 s46, s46, 0x80
	s_addc_u32 s47, s47, 0
	v_mfma_f32_32x32x16_bf16 v[0:15], v[152:155], v[160:163], v[0:15]
	ds_read_b128 v[144:147], v173 offset:0
	v_mfma_f32_32x32x16_bf16 v[16:31], v[152:155], v[164:167], v[16:31]
	ds_read_b128 v[136:139], v169 offset:0
	s_add_u32 m0, s51, 0x10000
	s_nop 0
	global_load_lds_dwordx4 v182, s[48:49]
	v_mfma_f32_32x32x16_bf16 v[32:47], v[156:159], v[160:163], v[32:47]
	ds_read_b128 v[148:151], v173 offset:4096
	v_mfma_f32_32x32x16_bf16 v[48:63], v[156:159], v[164:167], v[48:63]
	ds_read_b128 v[140:143], v169 offset:4096
	s_add_u32 m0, s51, 0x10400
	s_nop 0
	global_load_lds_dwordx4 v183, s[48:49]
	s_waitcnt lgkmcnt(6)
	v_mfma_f32_32x32x16_bf16 v[0:15], v[120:123], v[128:131], v[0:15]
	ds_read_b128 v[160:163], v174 offset:0
	s_waitcnt lgkmcnt(6)
	v_mfma_f32_32x32x16_bf16 v[16:31], v[120:123], v[132:135], v[16:31]
	ds_read_b128 v[152:155], v170 offset:0
	s_add_u32 m0, s51, 0x10800
	s_nop 0
	global_load_lds_dwordx4 v184, s[48:49]
	s_waitcnt lgkmcnt(6)
	v_mfma_f32_32x32x16_bf16 v[32:47], v[124:127], v[128:131], v[32:47]
	ds_read_b128 v[164:167], v174 offset:4096
	v_mfma_f32_32x32x16_bf16 v[48:63], v[124:127], v[132:135], v[48:63]
	ds_read_b128 v[156:159], v170 offset:4096
	s_add_u32 m0, s51, 0x10c00
	s_nop 0
	global_load_lds_dwordx4 v185, s[48:49]
	s_add_u32 s48, s48, 0x80
	s_addc_u32 s49, s49, 0
	ds_read_b128 v[128:131], v175 offset:0
	ds_read_b128 v[120:123], v171 offset:0
	ds_read_b128 v[132:135], v175 offset:4096
	ds_read_b128 v[124:127], v171 offset:4096
	s_waitcnt lgkmcnt(10)
	v_mfma_f32_32x32x16_bf16 v[0:15], v[136:139], v[144:147], v[0:15]
	s_waitcnt lgkmcnt(9)
	v_mfma_f32_32x32x16_bf16 v[16:31], v[136:139], v[148:151], v[16:31]
	s_waitcnt lgkmcnt(8)
	v_mfma_f32_32x32x16_bf16 v[32:47], v[140:143], v[144:147], v[32:47]
	v_mfma_f32_32x32x16_bf16 v[48:63], v[140:143], v[148:151], v[48:63]
	s_waitcnt vmcnt(6) lgkmcnt(0)
	s_barrier
	v_mfma_f32_32x32x16_bf16 v[0:15], v[152:155], v[160:163], v[0:15]
	ds_read_b128 v[144:147], v172 offset:32768
	v_mfma_f32_32x32x16_bf16 v[16:31], v[152:155], v[164:167], v[16:31]
	ds_read_b128 v[136:139], v168 offset:16384
	s_mov_b32 m0, s50
	s_nop 0
	global_load_lds_dwordx4 v180, s[46:47]
	v_mfma_f32_32x32x16_bf16 v[32:47], v[156:159], v[160:163], v[32:47]
	ds_read_b128 v[148:151], v172 offset:36864
	v_mfma_f32_32x32x16_bf16 v[48:63], v[156:159], v[164:167], v[48:63]
	ds_read_b128 v[140:143], v168 offset:20480
	s_add_u32 m0, s50, 0x400
	s_nop 0
	global_load_lds_dwordx4 v181, s[46:47]
	s_add_u32 s46, s46, 0x80
	s_addc_u32 s47, s47, 0
	v_mfma_f32_32x32x16_bf16 v[0:15], v[120:123], v[128:131], v[0:15]
	ds_read_b128 v[160:163], v173 offset:32768
	v_mfma_f32_32x32x16_bf16 v[16:31], v[120:123], v[132:135], v[16:31]
	ds_read_b128 v[152:155], v169 offset:16384
	s_mov_b32 m0, s51
	s_nop 0
	global_load_lds_dwordx4 v182, s[48:49]
	v_mfma_f32_32x32x16_bf16 v[32:47], v[124:127], v[128:131], v[32:47]
	ds_read_b128 v[164:167], v173 offset:36864
	v_mfma_f32_32x32x16_bf16 v[48:63], v[124:127], v[132:135], v[48:63]
	ds_read_b128 v[156:159], v169 offset:20480
	s_add_u32 m0, s51, 0x400
	s_nop 0
	global_load_lds_dwordx4 v183, s[48:49]
	s_waitcnt lgkmcnt(6)
	v_mfma_f32_32x32x16_bf16 v[0:15], v[136:139], v[144:147], v[0:15]
	ds_read_b128 v[128:131], v174 offset:32768
	s_waitcnt lgkmcnt(6)
	v_mfma_f32_32x32x16_bf16 v[16:31], v[136:139], v[148:151], v[16:31]
	ds_read_b128 v[120:123], v170 offset:16384
	s_add_u32 m0, s51, 0x800
	s_nop 0
	global_load_lds_dwordx4 v184, s[48:49]
	s_waitcnt lgkmcnt(6)
	v_mfma_f32_32x32x16_bf16 v[32:47], v[140:143], v[144:147], v[32:47]
	ds_read_b128 v[132:135], v174 offset:36864
	v_mfma_f32_32x32x16_bf16 v[48:63], v[140:143], v[148:151], v[48:63]
	ds_read_b128 v[124:127], v170 offset:20480
	s_add_u32 m0, s51, 0xc00
	s_nop 0
	global_load_lds_dwordx4 v185, s[48:49]
	s_add_u32 s48, s48, 0x80
	s_addc_u32 s49, s49, 0
	ds_read_b128 v[144:147], v175 offset:32768
	ds_read_b128 v[136:139], v171 offset:16384
	ds_read_b128 v[148:151], v175 offset:36864
	ds_read_b128 v[140:143], v171 offset:20480
	s_waitcnt lgkmcnt(10)
	v_mfma_f32_32x32x16_bf16 v[0:15], v[152:155], v[160:163], v[0:15]
	s_waitcnt lgkmcnt(9)
	v_mfma_f32_32x32x16_bf16 v[16:31], v[152:155], v[164:167], v[16:31]
	s_waitcnt lgkmcnt(8)
	v_mfma_f32_32x32x16_bf16 v[32:47], v[156:159], v[160:163], v[32:47]
	v_mfma_f32_32x32x16_bf16 v[48:63], v[156:159], v[164:167], v[48:63]
	s_waitcnt vmcnt(6) lgkmcnt(0)
	s_barrier
; #define MFMA32(a, b, c) __builtin_amdgcn_mfma_f32_32x32x16_bf16((a), (b), (c), 0, 0, 0)
; DI void gemm_mid(const bf16_t* __restrict__ W, int ldw, const bf16_t* __restrict__ X, size_t ldx, int mclamp, int kts,
;                  int nkt, int m0, f32x16 (&acc)[2][2], bf16_t* lds) {
;     ...
;   for (int kt = 0; kt < nkt; ++kt) {
;     const bool more = kt + 1 < nkt;
;     if (more) GM_GLOAD(kt + 1)
;     __builtin_amdgcn_sched_barrier(0);
;     {
;       const bf16_t* wb = lds + (kt & 1) * MID_E + (wn * 64 + lr) * LDT + lh * 8;
;       const bf16_t* xb = lds + (kt & 1) * MID_E + 128 * LDT + (wm * 64 + lr) * LDT + lh * 8;
; #pragma unroll
;       for (int ks = 0; ks < 4; ++ks) {
;         const bf16x8 a0 = *(const bf16x8*)(wb + ks * 16), a1 = *(const bf16x8*)(wb + 32 * LDT + ks * 16);
;         const bf16x8 b0 = *(const bf16x8*)(xb + ks * 16), b1 = *(const bf16x8*)(xb + 32 * LDT + ks * 16);
;         acc[0][0] = MFMA32(a0, b0, acc[0][0]); acc[0][1] = MFMA32(a0, b1, acc[0][1]);
;         acc[1][0] = MFMA32(a1, b0, acc[1][0]); acc[1][1] = MFMA32(a1, b1, acc[1][1]);
;       }
;     }
;     __builtin_amdgcn_sched_barrier(0);
;     if (more) GM_LSTORE((kt + 1) & 1)
;     __syncthreads();
;   }
	v_mfma_f32_32x32x16_bf16 v[0:15], v[120:123], v[128:131], v[0:15]
	ds_read_b128 v[160:163], v176 offset:0
	v_mfma_f32_32x32x16_bf16 v[16:31], v[120:123], v[132:135], v[16:31]
	ds_read_b128 v[152:155], v168 offset:32768
	s_add_u32 m0, s50, 0x4000
	s_nop 0
	global_load_lds_dwordx4 v180, s[46:47]
	v_mfma_f32_32x32x16_bf16 v[32:47], v[124:127], v[128:131], v[32:47]
	ds_read_b128 v[164:167], v176 offset:4096
	v_mfma_f32_32x32x16_bf16 v[48:63], v[124:127], v[132:135], v[48:63]
	ds_read_b128 v[156:159], v168 offset:36864
	s_add_u32 m0, s50, 0x4400
	s_nop 0
	global_load_lds_dwordx4 v181, s[46:47]
	s_add_u32 s46, s46, 0x80
	s_addc_u32 s47, s47, 0
	v_mfma_f32_32x32x16_bf16 v[0:15], v[136:139], v[144:147], v[0:15]
	ds_read_b128 v[128:131], v177 offset:0
	v_mfma_f32_32x32x16_bf16 v[16:31], v[136:139], v[148:151], v[16:31]
	ds_read_b128 v[120:123], v169 offset:32768
	s_add_u32 m0, s51, 0x8000
	s_nop 0
	global_load_lds_dwordx4 v182, s[48:49]
	v_mfma_f32_32x32x16_bf16 v[32:47], v[140:143], v[144:147], v[32:47]
	ds_read_b128 v[132:135], v177 offset:4096
	v_mfma_f32_32x32x16_bf16 v[48:63], v[140:143], v[148:151], v[48:63]
	ds_read_b128 v[124:127], v169 offset:36864
	s_add_u32 m0, s51, 0x8400
	s_nop 0
	global_load_lds_dwordx4 v183, s[48:49]
	s_waitcnt lgkmcnt(6)
	v_mfma_f32_32x32x16_bf16 v[0:15], v[152:155], v[160:163], v[0:15]
	ds_read_b128 v[144:147], v178 offset:0
	s_waitcnt lgkmcnt(6)
	v_mfma_f32_32x32x16_bf16 v[16:31], v[152:155], v[164:167], v[16:31]
	ds_read_b128 v[136:139], v170 offset:32768
	s_add_u32 m0, s51, 0x8800
	s_nop 0
	global_load_lds_dwordx4 v184, s[48:49]
	s_waitcnt lgkmcnt(6)
	v_mfma_f32_32x32x16_bf16 v[32:47], v[156:159], v[160:163], v[32:47]
	ds_read_b128 v[148:151], v178 offset:4096
	v_mfma_f32_32x32x16_bf16 v[48:63], v[156:159], v[164:167], v[48:63]
	ds_read_b128 v[140:143], v170 offset:36864
	s_add_u32 m0, s51, 0x8c00
	s_nop 0
	global_load_lds_dwordx4 v185, s[48:49]
	s_add_u32 s48, s48, 0x80
	s_addc_u32 s49, s49, 0
	ds_read_b128 v[160:163], v179 offset:0
	ds_read_b128 v[152:155], v171 offset:32768
	ds_read_b128 v[164:167], v179 offset:4096
	ds_read_b128 v[156:159], v171 offset:36864
	s_waitcnt lgkmcnt(10)
	v_mfma_f32_32x32x16_bf16 v[0:15], v[120:123], v[128:131], v[0:15]
	s_waitcnt lgkmcnt(9)
	v_mfma_f32_32x32x16_bf16 v[16:31], v[120:123], v[132:135], v[16:31]
	s_waitcnt lgkmcnt(8)
	v_mfma_f32_32x32x16_bf16 v[32:47], v[124:127], v[128:131], v[32:47]
	v_mfma_f32_32x32x16_bf16 v[48:63], v[124:127], v[132:135], v[48:63]
	s_waitcnt vmcnt(6) lgkmcnt(0)
	s_barrier
	v_mfma_f32_32x32x16_bf16 v[0:15], v[136:139], v[144:147], v[0:15]
	ds_read_b128 v[128:131], v172 offset:0
	v_mfma_f32_32x32x16_bf16 v[16:31], v[136:139], v[148:151], v[16:31]
	ds_read_b128 v[120:123], v168 offset:0
	v_mfma_f32_32x32x16_bf16 v[32:47], v[140:143], v[144:147], v[32:47]
	ds_read_b128 v[132:135], v172 offset:4096
	v_mfma_f32_32x32x16_bf16 v[48:63], v[140:143], v[148:151], v[48:63]
	ds_read_b128 v[124:127], v168 offset:4096
	v_mfma_f32_32x32x16_bf16 v[0:15], v[152:155], v[160:163], v[0:15]
	ds_read_b128 v[144:147], v173 offset:0
	v_mfma_f32_32x32x16_bf16 v[16:31], v[152:155], v[164:167], v[16:31]
	ds_read_b128 v[136:139], v169 offset:0
	v_mfma_f32_32x32x16_bf16 v[32:47], v[156:159], v[160:163], v[32:47]
	ds_read_b128 v[148:151], v173 offset:4096
	v_mfma_f32_32x32x16_bf16 v[48:63], v[156:159], v[164:167], v[48:63]
	ds_read_b128 v[140:143], v169 offset:4096
	s_waitcnt lgkmcnt(6)
	v_mfma_f32_32x32x16_bf16 v[0:15], v[120:123], v[128:131], v[0:15]
	ds_read_b128 v[160:163], v174 offset:0
	s_waitcnt lgkmcnt(6)
	v_mfma_f32_32x32x16_bf16 v[16:31], v[120:123], v[132:135], v[16:31]
	ds_read_b128 v[152:155], v170 offset:0
	s_waitcnt lgkmcnt(6)
	v_mfma_f32_32x32x16_bf16 v[32:47], v[124:127], v[128:131], v[32:47]
	ds_read_b128 v[164:167], v174 offset:4096
	v_mfma_f32_32x32x16_bf16 v[48:63], v[124:127], v[132:135], v[48:63]
	ds_read_b128 v[156:159], v170 offset:4096
	ds_read_b128 v[128:131], v175 offset:0
	ds_read_b128 v[120:123], v171 offset:0
	ds_read_b128 v[132:135], v175 offset:4096
	ds_read_b128 v[124:127], v171 offset:4096
	s_waitcnt lgkmcnt(10)
	v_mfma_f32_32x32x16_bf16 v[0:15], v[136:139], v[144:147], v[0:15]
	s_waitcnt lgkmcnt(9)
	v_mfma_f32_32x32x16_bf16 v[16:31], v[136:139], v[148:151], v[16:31]
	s_waitcnt lgkmcnt(8)
	v_mfma_f32_32x32x16_bf16 v[32:47], v[140:143], v[144:147], v[32:47]
	v_mfma_f32_32x32x16_bf16 v[48:63], v[140:143], v[148:151], v[48:63]
	s_waitcnt vmcnt(0) lgkmcnt(0)
	s_barrier
	v_mfma_f32_32x32x16_bf16 v[0:15], v[152:155], v[160:163], v[0:15]
	ds_read_b128 v[144:147], v172 offset:32768
	v_mfma_f32_32x32x16_bf16 v[16:31], v[152:155], v[164:167], v[16:31]
	ds_read_b128 v[136:139], v168 offset:16384
	v_mfma_f32_32x32x16_bf16 v[32:47], v[156:159], v[160:163], v[32:47]
	ds_read_b128 v[148:151], v172 offset:36864
	v_mfma_f32_32x32x16_bf16 v[48:63], v[156:159], v[164:167], v[48:63]
	ds_read_b128 v[140:143], v168 offset:20480
	v_mfma_f32_32x32x16_bf16 v[0:15], v[120:123], v[128:131], v[0:15]
	ds_read_b128 v[160:163], v173 offset:32768
	v_mfma_f32_32x32x16_bf16 v[16:31], v[120:123], v[132:135], v[16:31]
	ds_read_b128 v[152:155], v169 offset:16384
	v_mfma_f32_32x32x16_bf16 v[32:47], v[124:127], v[128:131], v[32:47]
	ds_read_b128 v[164:167], v173 offset:36864
	v_mfma_f32_32x32x16_bf16 v[48:63], v[124:127], v[132:135], v[48:63]
	ds_read_b128 v[156:159], v169 offset:20480
	s_waitcnt lgkmcnt(6)
	v_mfma_f32_32x32x16_bf16 v[0:15], v[136:139], v[144:147], v[0:15]
	ds_read_b128 v[128:131], v174 offset:32768
	s_waitcnt lgkmcnt(6)
	v_mfma_f32_32x32x16_bf16 v[16:31], v[136:139], v[148:151], v[16:31]
	ds_read_b128 v[120:123], v170 offset:16384
	s_waitcnt lgkmcnt(6)
	v_mfma_f32_32x32x16_bf16 v[32:47], v[140:143], v[144:147], v[32:47]
	ds_read_b128 v[132:135], v174 offset:36864
	v_mfma_f32_32x32x16_bf16 v[48:63], v[140:143], v[148:151], v[48:63]
	ds_read_b128 v[124:127], v170 offset:20480
	ds_read_b128 v[144:147], v175 offset:32768
	ds_read_b128 v[136:139], v171 offset:16384
	ds_read_b128 v[148:151], v175 offset:36864
	ds_read_b128 v[140:143], v171 offset:20480
	s_waitcnt lgkmcnt(10)
	v_mfma_f32_32x32x16_bf16 v[0:15], v[152:155], v[160:163], v[0:15]
	s_waitcnt lgkmcnt(9)
	v_mfma_f32_32x32x16_bf16 v[16:31], v[152:155], v[164:167], v[16:31]
	s_waitcnt lgkmcnt(8)
	v_mfma_f32_32x32x16_bf16 v[32:47], v[156:159], v[160:163], v[32:47]
	v_mfma_f32_32x32x16_bf16 v[48:63], v[156:159], v[164:167], v[48:63]
	s_waitcnt lgkmcnt(0)
	s_barrier
; #define MFMA32(a, b, c) __builtin_amdgcn_mfma_f32_32x32x16_bf16((a), (b), (c), 0, 0, 0)
; DI float bf2f(bf16_t b) { return __uint_as_float(((unsigned)b) << 16); }
; DI unsigned pack2(float a, float b) { f32x2_t v = {a, b}; bf16x2_t r = __builtin_convertvector(v, bf16x2_t); return __builtin_bit_cast(unsigned, r); }
; DI void gemm_mid(const bf16_t* __restrict__ W, int ldw, const bf16_t* __restrict__ X, size_t ldx, int mclamp, int kts,
;                  int nkt, int m0, f32x16 (&acc)[2][2], bf16_t* lds) {
;     ...
;       for (int ks = 0; ks < 4; ++ks) {
;         const bf16x8 a0 = *(const bf16x8*)(wb + ks * 16), a1 = *(const bf16x8*)(wb + 32 * LDT + ks * 16);
;         const bf16x8 b0 = *(const bf16x8*)(xb + ks * 16), b1 = *(const bf16x8*)(xb + 32 * LDT + ks * 16);
;         acc[0][0] = MFMA32(a0, b0, acc[0][0]); acc[0][1] = MFMA32(a0, b1, acc[0][1]);
;         acc[1][0] = MFMA32(a1, b0, acc[1][0]); acc[1][1] = MFMA32(a1, b1, acc[1][1]);
;       }
; DI void phase_merge(const P& p, int layer, bf16_t* sm, const Geo& ge) {
;     ...
; #pragma unroll
;       for (int mt = 0; mt < 2; ++mt) {
;         const int m = mt_ * 256 + wm * 64 + mt * 32 + lr;
; #pragma unroll
;         for (int nt = 0; nt < 2; ++nt)
; #pragma unroll
;           for (int qd = 0; qd < 4; ++qd) {
;             const int n = nt_ * 128 + wn * 64 + nt * 32 + 8 * qd + 4 * lh;
;             typedef unsigned u32x2_t __attribute__((ext_vector_type(2)));
;             const u32x2_t gq_ = __builtin_nontemporal_load((const u32x2_t*)(mgs + ((size_t)((n3 * 1024 + n) >> 2) * T_ + m) * 4));
;             const uint2 gq = make_uint2(gq_[0], gq_[1]);
;             const unsigned z01 = zp[nt][mt][2 * qd], z23 = zp[nt][mt][2 * qd + 1];
;             const float v0 = bf2f((bf16_t)(z01 & 0xffff)) + bf2f((bf16_t)(gq.x & 0xffff)) * acc[nt][mt][4 * qd];
;             const float v1 = bf2f((bf16_t)(z01 >> 16)) + bf2f((bf16_t)(gq.x >> 16)) * acc[nt][mt][4 * qd + 1];
;             const float v2 = bf2f((bf16_t)(z23 & 0xffff)) + bf2f((bf16_t)(gq.y & 0xffff)) * acc[nt][mt][4 * qd + 2];
;             const float v3 = bf2f((bf16_t)(z23 >> 16)) + bf2f((bf16_t)(gq.y >> 16)) * acc[nt][mt][4 * qd + 3];
;             zp[nt][mt][2 * qd] = pack2(v0, v1);
;             zp[nt][mt][2 * qd + 1] = pack2(v2, v3);
;           }
	v_mfma_f32_32x32x16_bf16 v[0:15], v[120:123], v[128:131], v[0:15]
	v_mfma_f32_32x32x16_bf16 v[16:31], v[120:123], v[132:135], v[16:31]
	v_mfma_f32_32x32x16_bf16 v[32:47], v[124:127], v[128:131], v[32:47]
	v_mfma_f32_32x32x16_bf16 v[48:63], v[124:127], v[132:135], v[48:63]
	v_mfma_f32_32x32x16_bf16 v[0:15], v[136:139], v[144:147], v[0:15]
	v_mfma_f32_32x32x16_bf16 v[16:31], v[136:139], v[148:151], v[16:31]
	v_mfma_f32_32x32x16_bf16 v[32:47], v[140:143], v[144:147], v[32:47]
	v_mfma_f32_32x32x16_bf16 v[48:63], v[140:143], v[148:151], v[48:63]
	s_nop 15
	v_lshlrev_b32_e32 v98, 16, v196
	v_and_b32_e32 v99, 0xffff0000, v196
	v_lshlrev_b32_e32 v100, 16, v197
	v_and_b32_e32 v101, 0xffff0000, v197
	v_lshlrev_b32_e32 v102, 16, v64
	v_and_b32_e32 v103, 0xffff0000, v64
	v_lshlrev_b32_e32 v104, 16, v65
	v_and_b32_e32 v105, 0xffff0000, v65
	v_fma_f32 v98, v0, v98, v102
	v_fma_f32 v99, v1, v99, v103
	v_fma_f32 v100, v2, v100, v104
	v_fma_f32 v101, v3, v101, v105
	v_cvt_pk_bf16_f32 v64, v98, v99
	v_cvt_pk_bf16_f32 v65, v100, v101
	v_lshlrev_b32_e32 v98, 16, v198
	v_and_b32_e32 v99, 0xffff0000, v198
	v_lshlrev_b32_e32 v100, 16, v199
	v_and_b32_e32 v101, 0xffff0000, v199
	v_lshlrev_b32_e32 v102, 16, v66
	v_and_b32_e32 v103, 0xffff0000, v66
	v_lshlrev_b32_e32 v104, 16, v67
	v_and_b32_e32 v105, 0xffff0000, v67
	v_fma_f32 v98, v4, v98, v102
	v_fma_f32 v99, v5, v99, v103
	v_fma_f32 v100, v6, v100, v104
	v_fma_f32 v101, v7, v101, v105
	v_cvt_pk_bf16_f32 v66, v98, v99
	v_cvt_pk_bf16_f32 v67, v100, v101
	v_lshlrev_b32_e32 v98, 16, v200
	v_and_b32_e32 v99, 0xffff0000, v200
	v_lshlrev_b32_e32 v100, 16, v201
	v_and_b32_e32 v101, 0xffff0000, v201
	v_lshlrev_b32_e32 v102, 16, v68
	v_and_b32_e32 v103, 0xffff0000, v68
	v_lshlrev_b32_e32 v104, 16, v69
	v_and_b32_e32 v105, 0xffff0000, v69
	v_fma_f32 v98, v8, v98, v102
	v_fma_f32 v99, v9, v99, v103
	v_fma_f32 v100, v10, v100, v104
	v_fma_f32 v101, v11, v101, v105
	v_cvt_pk_bf16_f32 v68, v98, v99
	v_cvt_pk_bf16_f32 v69, v100, v101
	v_lshlrev_b32_e32 v98, 16, v202
	v_and_b32_e32 v99, 0xffff0000, v202
	v_lshlrev_b32_e32 v100, 16, v203
	v_and_b32_e32 v101, 0xffff0000, v203
	v_lshlrev_b32_e32 v102, 16, v70
	v_and_b32_e32 v103, 0xffff0000, v70
	v_lshlrev_b32_e32 v104, 16, v71
	v_and_b32_e32 v105, 0xffff0000, v71
	v_fma_f32 v98, v12, v98, v102
	v_fma_f32 v99, v13, v99, v103
	v_fma_f32 v100, v14, v100, v104
	v_fma_f32 v101, v15, v101, v105
	v_cvt_pk_bf16_f32 v70, v98, v99
	v_cvt_pk_bf16_f32 v71, v100, v101
	v_lshlrev_b32_e32 v98, 16, v204
	v_and_b32_e32 v99, 0xffff0000, v204
	v_lshlrev_b32_e32 v100, 16, v205
	v_and_b32_e32 v101, 0xffff0000, v205
	v_lshlrev_b32_e32 v102, 16, v72
	v_and_b32_e32 v103, 0xffff0000, v72
	v_lshlrev_b32_e32 v104, 16, v73
	v_and_b32_e32 v105, 0xffff0000, v73
	v_fma_f32 v98, v32, v98, v102
	v_fma_f32 v99, v33, v99, v103
	v_fma_f32 v100, v34, v100, v104
	v_fma_f32 v101, v35, v101, v105
	v_cvt_pk_bf16_f32 v72, v98, v99
	v_cvt_pk_bf16_f32 v73, v100, v101
	v_lshlrev_b32_e32 v98, 16, v206
	v_and_b32_e32 v99, 0xffff0000, v206
	v_lshlrev_b32_e32 v100, 16, v207
	v_and_b32_e32 v101, 0xffff0000, v207
	v_lshlrev_b32_e32 v102, 16, v74
	v_and_b32_e32 v103, 0xffff0000, v74
	v_lshlrev_b32_e32 v104, 16, v75
	v_and_b32_e32 v105, 0xffff0000, v75
	v_fma_f32 v98, v36, v98, v102
	v_fma_f32 v99, v37, v99, v103
	v_fma_f32 v100, v38, v100, v104
	v_fma_f32 v101, v39, v101, v105
	v_cvt_pk_bf16_f32 v74, v98, v99
	v_cvt_pk_bf16_f32 v75, v100, v101
	v_lshlrev_b32_e32 v98, 16, v208
	v_and_b32_e32 v99, 0xffff0000, v208
	v_lshlrev_b32_e32 v100, 16, v209
	v_and_b32_e32 v101, 0xffff0000, v209
	v_lshlrev_b32_e32 v102, 16, v76
	v_and_b32_e32 v103, 0xffff0000, v76
	v_lshlrev_b32_e32 v104, 16, v77
	v_and_b32_e32 v105, 0xffff0000, v77
	v_fma_f32 v98, v40, v98, v102
	v_fma_f32 v99, v41, v99, v103
	v_fma_f32 v100, v42, v100, v104
	v_fma_f32 v101, v43, v101, v105
	v_cvt_pk_bf16_f32 v76, v98, v99
	v_cvt_pk_bf16_f32 v77, v100, v101
	v_lshlrev_b32_e32 v98, 16, v210
	v_and_b32_e32 v99, 0xffff0000, v210
	v_lshlrev_b32_e32 v100, 16, v211
	v_and_b32_e32 v101, 0xffff0000, v211
	v_lshlrev_b32_e32 v102, 16, v78
	v_and_b32_e32 v103, 0xffff0000, v78
	v_lshlrev_b32_e32 v104, 16, v79
	v_and_b32_e32 v105, 0xffff0000, v79
	v_fma_f32 v98, v44, v98, v102
	v_fma_f32 v99, v45, v99, v103
	v_fma_f32 v100, v46, v100, v104
	v_fma_f32 v101, v47, v101, v105
	v_cvt_pk_bf16_f32 v78, v98, v99
	v_cvt_pk_bf16_f32 v79, v100, v101
	v_lshlrev_b32_e32 v98, 16, v212
	v_and_b32_e32 v99, 0xffff0000, v212
	v_lshlrev_b32_e32 v100, 16, v213
	v_and_b32_e32 v101, 0xffff0000, v213
	v_lshlrev_b32_e32 v102, 16, v80
	v_and_b32_e32 v103, 0xffff0000, v80
	v_lshlrev_b32_e32 v104, 16, v81
	v_and_b32_e32 v105, 0xffff0000, v81
	v_fma_f32 v98, v16, v98, v102
	v_fma_f32 v99, v17, v99, v103
	v_fma_f32 v100, v18, v100, v104
	v_fma_f32 v101, v19, v101, v105
	v_cvt_pk_bf16_f32 v80, v98, v99
	v_cvt_pk_bf16_f32 v81, v100, v101
	v_lshlrev_b32_e32 v98, 16, v214
	v_and_b32_e32 v99, 0xffff0000, v214
	v_lshlrev_b32_e32 v100, 16, v215
	v_and_b32_e32 v101, 0xffff0000, v215
	v_lshlrev_b32_e32 v102, 16, v82
	v_and_b32_e32 v103, 0xffff0000, v82
; DI float bf2f(bf16_t b) { return __uint_as_float(((unsigned)b) << 16); }
; DI unsigned pack2(float a, float b) { f32x2_t v = {a, b}; bf16x2_t r = __builtin_convertvector(v, bf16x2_t); return __builtin_bit_cast(unsigned, r); }
; DI void phase_merge(const P& p, int layer, bf16_t* sm, const Geo& ge) {
;     ...
;             const u32x2_t gq_ = __builtin_nontemporal_load((const u32x2_t*)(mgs + ((size_t)((n3 * 1024 + n) >> 2) * T_ + m) * 4));
;             const uint2 gq = make_uint2(gq_[0], gq_[1]);
;             const unsigned z01 = zp[nt][mt][2 * qd], z23 = zp[nt][mt][2 * qd + 1];
;             const float v0 = bf2f((bf16_t)(z01 & 0xffff)) + bf2f((bf16_t)(gq.x & 0xffff)) * acc[nt][mt][4 * qd];
;             const float v1 = bf2f((bf16_t)(z01 >> 16)) + bf2f((bf16_t)(gq.x >> 16)) * acc[nt][mt][4 * qd + 1];
;             const float v2 = bf2f((bf16_t)(z23 & 0xffff)) + bf2f((bf16_t)(gq.y & 0xffff)) * acc[nt][mt][4 * qd + 2];
;             const float v3 = bf2f((bf16_t)(z23 >> 16)) + bf2f((bf16_t)(gq.y >> 16)) * acc[nt][mt][4 * qd + 3];
;             zp[nt][mt][2 * qd] = pack2(v0, v1);
;             zp[nt][mt][2 * qd + 1] = pack2(v2, v3);
;           }
;       }
;     }
;     bf16_t* stg = sm + wv * (64 * 72);
; #pragma unroll
;     for (int mt = 0; mt < 2; ++mt)
; #pragma unroll
;       for (int nt = 0; nt < 2; ++nt)
; #pragma unroll
;         for (int qd = 0; qd < 4; ++qd)
;           *(uint2*)(stg + (mt * 32 + lr) * 72 + nt * 32 + 8 * qd + 4 * lh) = make_uint2(zp[nt][mt][2 * qd], zp[nt][mt][2 * qd + 1]);
; #pragma unroll
;     for (int it = 0; it < 8; ++it) {
;       const int row = it * 8 + (lane >> 3), c16 = lane & 7;
;       const u32x4 v = *(const u32x4*)(stg + row * 72 + c16 * 8);
;       *(u32x4*)(z + (size_t)(mt_ * 256 + wm * 64 + row) * LDK1 + nt_ * 128 + wn * 64 + c16 * 8) = v;
	v_lshlrev_b32_e32 v104, 16, v83
	v_and_b32_e32 v105, 0xffff0000, v83
	v_fma_f32 v98, v20, v98, v102
	v_fma_f32 v99, v21, v99, v103
	v_fma_f32 v100, v22, v100, v104
	v_fma_f32 v101, v23, v101, v105
	v_cvt_pk_bf16_f32 v82, v98, v99
	v_cvt_pk_bf16_f32 v83, v100, v101
	v_lshlrev_b32_e32 v98, 16, v216
	v_and_b32_e32 v99, 0xffff0000, v216
	v_lshlrev_b32_e32 v100, 16, v217
	v_and_b32_e32 v101, 0xffff0000, v217
	v_lshlrev_b32_e32 v102, 16, v84
	v_and_b32_e32 v103, 0xffff0000, v84
	v_lshlrev_b32_e32 v104, 16, v85
	v_and_b32_e32 v105, 0xffff0000, v85
	v_fma_f32 v98, v24, v98, v102
	v_fma_f32 v99, v25, v99, v103
	v_fma_f32 v100, v26, v100, v104
	v_fma_f32 v101, v27, v101, v105
	v_cvt_pk_bf16_f32 v84, v98, v99
	v_cvt_pk_bf16_f32 v85, v100, v101
	v_lshlrev_b32_e32 v98, 16, v218
	v_and_b32_e32 v99, 0xffff0000, v218
	v_lshlrev_b32_e32 v100, 16, v219
	v_and_b32_e32 v101, 0xffff0000, v219
	v_lshlrev_b32_e32 v102, 16, v86
	v_and_b32_e32 v103, 0xffff0000, v86
	v_lshlrev_b32_e32 v104, 16, v87
	v_and_b32_e32 v105, 0xffff0000, v87
	v_fma_f32 v98, v28, v98, v102
	v_fma_f32 v99, v29, v99, v103
	v_fma_f32 v100, v30, v100, v104
	v_fma_f32 v101, v31, v101, v105
	v_cvt_pk_bf16_f32 v86, v98, v99
	v_cvt_pk_bf16_f32 v87, v100, v101
	v_lshlrev_b32_e32 v98, 16, v236
	v_and_b32_e32 v99, 0xffff0000, v236
	v_lshlrev_b32_e32 v100, 16, v237
	v_and_b32_e32 v101, 0xffff0000, v237
	v_lshlrev_b32_e32 v102, 16, v90
	v_and_b32_e32 v103, 0xffff0000, v90
	v_lshlrev_b32_e32 v104, 16, v91
	v_and_b32_e32 v105, 0xffff0000, v91
	v_fma_f32 v98, v48, v98, v102
	v_fma_f32 v99, v49, v99, v103
	v_fma_f32 v100, v50, v100, v104
	v_fma_f32 v101, v51, v101, v105
	v_cvt_pk_bf16_f32 v90, v98, v99
	v_cvt_pk_bf16_f32 v91, v100, v101
	v_lshlrev_b32_e32 v98, 16, v238
	v_and_b32_e32 v99, 0xffff0000, v238
	v_lshlrev_b32_e32 v100, 16, v239
	v_and_b32_e32 v101, 0xffff0000, v239
	v_lshlrev_b32_e32 v102, 16, v92
	v_and_b32_e32 v103, 0xffff0000, v92
	v_lshlrev_b32_e32 v104, 16, v93
	v_and_b32_e32 v105, 0xffff0000, v93
	v_fma_f32 v98, v52, v98, v102
	v_fma_f32 v99, v53, v99, v103
	v_fma_f32 v100, v54, v100, v104
	v_fma_f32 v101, v55, v101, v105
	v_cvt_pk_bf16_f32 v92, v98, v99
	v_cvt_pk_bf16_f32 v93, v100, v101
	v_lshlrev_b32_e32 v98, 16, v240
	v_and_b32_e32 v99, 0xffff0000, v240
	v_lshlrev_b32_e32 v100, 16, v241
	v_and_b32_e32 v101, 0xffff0000, v241
	v_lshlrev_b32_e32 v102, 16, v94
	v_and_b32_e32 v103, 0xffff0000, v94
	v_lshlrev_b32_e32 v104, 16, v95
	v_and_b32_e32 v105, 0xffff0000, v95
	v_fma_f32 v98, v56, v98, v102
	v_fma_f32 v99, v57, v99, v103
	v_fma_f32 v100, v58, v100, v104
	v_fma_f32 v101, v59, v101, v105
	v_cvt_pk_bf16_f32 v94, v98, v99
	v_cvt_pk_bf16_f32 v95, v100, v101
	v_lshlrev_b32_e32 v98, 16, v242
	v_and_b32_e32 v99, 0xffff0000, v242
	v_lshlrev_b32_e32 v100, 16, v243
	v_and_b32_e32 v101, 0xffff0000, v243
	v_lshlrev_b32_e32 v102, 16, v96
	v_and_b32_e32 v103, 0xffff0000, v96
	v_lshlrev_b32_e32 v104, 16, v97
	v_and_b32_e32 v105, 0xffff0000, v97
	v_fma_f32 v98, v60, v98, v102
	v_fma_f32 v99, v61, v99, v103
	v_fma_f32 v100, v62, v100, v104
	v_fma_f32 v101, v63, v101, v105
	v_cvt_pk_bf16_f32 v96, v98, v99
	v_cvt_pk_bf16_f32 v97, v100, v101
	ds_write_b64 v188, v[64:65] offset:0
	ds_write_b64 v188, v[66:67] offset:16
	ds_write_b64 v188, v[68:69] offset:32
	ds_write_b64 v188, v[70:71] offset:48
	ds_write_b64 v188, v[72:73] offset:64
	ds_write_b64 v188, v[74:75] offset:80
	ds_write_b64 v188, v[76:77] offset:96
	ds_write_b64 v188, v[78:79] offset:112
	ds_write_b64 v188, v[80:81] offset:4608
	ds_write_b64 v188, v[82:83] offset:4624
	ds_write_b64 v188, v[84:85] offset:4640
	ds_write_b64 v188, v[86:87] offset:4656
	ds_write_b64 v188, v[90:91] offset:4672
	ds_write_b64 v188, v[92:93] offset:4688
	ds_write_b64 v188, v[94:95] offset:4704
	ds_write_b64 v188, v[96:97] offset:4720
	s_waitcnt lgkmcnt(0)
	ds_read_b128 v[120:123], v189 offset:0
	ds_read_b128 v[124:127], v189 offset:1152
	ds_read_b128 v[128:131], v189 offset:2304
	ds_read_b128 v[132:135], v189 offset:3456
	ds_read_b128 v[136:139], v189 offset:4608
	ds_read_b128 v[140:143], v189 offset:5760
	ds_read_b128 v[144:147], v189 offset:6912
	ds_read_b128 v[148:151], v189 offset:8064
	s_waitcnt lgkmcnt(7)
	global_store_dwordx4 v187, v[120:123], s[56:57]
	s_waitcnt lgkmcnt(6)
	v_add_u32_e32 v187, 0x4400, v187
	global_store_dwordx4 v187, v[124:127], s[56:57]
	s_waitcnt lgkmcnt(5)
	v_add_u32_e32 v187, 0x4400, v187
	global_store_dwordx4 v187, v[128:131], s[56:57]
	s_waitcnt lgkmcnt(4)
	v_add_u32_e32 v187, 0x4400, v187
	global_store_dwordx4 v187, v[132:135], s[56:57]
	s_waitcnt lgkmcnt(3)
	v_add_u32_e32 v187, 0x4400, v187
	global_store_dwordx4 v187, v[136:139], s[56:57]
	s_waitcnt lgkmcnt(2)
	v_add_u32_e32 v187, 0x4400, v187
	global_store_dwordx4 v187, v[140:143], s[56:57]
	s_waitcnt lgkmcnt(1)
	v_add_u32_e32 v187, 0x4400, v187
	global_store_dwordx4 v187, v[144:147], s[56:57]
	s_waitcnt lgkmcnt(0)
	v_add_u32_e32 v187, 0x4400, v187
	global_store_dwordx4 v187, v[148:151], s[56:57]
	s_add_i32 s7, s7, s31
	s_add_i32 s6, s6, s36
	s_cmp_lt_i32 s8, 64
	s_cbranch_scc1 .LBB0_1090
